# QKRope q/k epilogue: the 8 row groups' sum-of-squares loads are all issued with the first one; groups 1..7 no longer drain vmcnt(0) (which also waited for the previous group's stores)
# baseline (speedup 1.0000x reference)
.LBB0_278:
	v_lshlrev_b64 v[130:131], 6, v[140:141]
	v_lshl_add_u64 v[130:131], s[96:97], 0, v[130:131]
	v_lshlrev_b64 v[144:145], 2, v[142:143]
	v_lshl_add_u64 v[130:131], v[130:131], 0, v[144:145]
	global_load_dwordx4 v[148:151], v[130:131], off
	s_mov_b64 s[98:99], 0x2000
	global_load_dwordx4 v[216:219], v[130:131], off offset:1024
	global_load_dwordx4 v[220:223], v[130:131], off offset:2048
	global_load_dwordx4 v[224:227], v[130:131], off offset:3072
	v_lshl_add_u64 v[244:245], v[130:131], 0, s[98:99]
	global_load_dwordx4 v[228:231], v[244:245], off
	global_load_dwordx4 v[232:235], v[244:245], off offset:1024
	global_load_dwordx4 v[236:239], v[244:245], off offset:2048
	global_load_dwordx4 v[240:243], v[244:245], off offset:3072
	s_cmp_eq_u32 s94, 4
	s_cselect_b64 vcc, -1, 0
	s_and_b64 s[20:21], vcc, exec
	s_mov_b32 s4, s64
	v_readlane_b32 s64, v251, 22
	s_mov_b32 s64, s4
	s_mov_b64 s[20:21], s[14:15]
	s_mov_b32 s27, s19
	s_mov_b32 s35, s8
	s_mov_b64 s[38:39], s[10:11]
	v_readlane_b32 s4, v251, 4
	v_readlane_b32 s10, v251, 10
	v_readlane_b32 s11, v251, 11
	v_and_b32_e32 v129, 1, v156
	s_mov_b64 s[10:11], s[38:39]
	v_cmp_eq_u32_e64 s[38:39], 0, v129
	v_add_u32_e32 v129, 12, v142
	v_readlane_b32 s78, v251, 36
	v_cndmask_b32_e64 v146, v129, v142, s[38:39]
	v_readlane_b32 s79, v251, 37
	v_readlane_b32 s5, v251, 5
	v_readlane_b32 s14, v251, 14
	v_readlane_b32 s15, v251, 15
	s_mov_b64 s[14:15], s[20:21]
	s_cselect_b32 s20, s5, s79
	s_cselect_b32 s21, s4, s78
	v_readlane_b32 s4, v254, 57
	v_readlane_b32 s5, v254, 58
	s_add_u32 s40, s21, s4
	s_addc_u32 s41, s20, s5
	v_readlane_b32 s4, v251, 53
	v_readlane_b32 s5, v251, 54
	s_mov_b64 s[20:21], s[40:41]
	v_and_b32_e32 v188, 0xfc0, v140
	v_cndmask_b32_e64 v128, v212, 1.0, vcc
	s_lshl_b32 s58, s94, 8
	s_ashr_i32 s59, s58, 31
	s_lshl_b64 s[58:59], s[58:59], 1
	v_ashrrev_i32_e32 v147, 31, v146
	v_readlane_b32 s8, v251, 8
	v_readlane_b32 s9, v251, 9
	v_readlane_b32 s18, v251, 18
	v_readlane_b32 s19, v251, 19
	s_mov_b32 s8, s35
	s_movk_i32 s9, 0x60
	s_mov_b32 s19, s27
	v_readlane_b32 s18, v251, 2
	v_readlane_b32 s65, v251, 23
	v_readlane_b32 s66, v251, 24
	v_readlane_b32 s67, v251, 25
	v_readlane_b32 s68, v251, 26
	v_readlane_b32 s69, v251, 27
	v_readlane_b32 s70, v251, 28
	v_readlane_b32 s71, v251, 29
	v_readlane_b32 s72, v251, 30
	v_readlane_b32 s73, v251, 31
	v_readlane_b32 s74, v251, 32
	v_readlane_b32 s75, v251, 33
	v_readlane_b32 s76, v251, 34
	v_readlane_b32 s77, v251, 35
	v_readlane_b32 s6, v251, 6
	v_readlane_b32 s7, v251, 7
	v_readlane_b32 s12, v251, 12
	v_readlane_b32 s13, v251, 13
	v_readlane_b32 s16, v251, 16
	v_readlane_b32 s17, v251, 17
	s_waitcnt vmcnt(0)
	v_mov_b32_e32 v130, v149
	v_mov_b32_e32 v131, v150
	v_mov_b32_e32 v149, v151
	v_pk_add_f32 v[130:131], v[130:131], v[148:149]
	s_nop 0
	v_add_f32_e32 v129, v130, v131
	ds_bpermute_b32 v130, v170, v129
	s_waitcnt lgkmcnt(0)
	v_add_f32_e32 v129, v129, v130
	ds_bpermute_b32 v130, v171, v129
	s_waitcnt lgkmcnt(0)
	v_add_f32_e32 v129, v129, v130
	v_fmamk_f32 v129, v129, 0x3a800000, v209
	v_cmp_gt_f32_e64 s[38:39], s0, v129
	v_mul_f32_e32 v130, 0x4b800000, v129
	s_nop 0
	v_cndmask_b32_e64 v129, v129, v130, s[38:39]
	v_rsq_f32_e32 v129, v129
	s_nop 0
	v_mul_f32_e32 v130, 0x45800000, v129
	v_cndmask_b32_e64 v130, v129, v130, s[38:39]
	v_pk_mul_f32 v[162:163], v[120:121], v[130:131] op_sel_hi:[1,0]
	v_pk_mul_f32 v[164:165], v[122:123], v[130:131] op_sel_hi:[1,0]
	v_pk_mul_f32 v[148:149], v[124:125], v[130:131] op_sel_hi:[1,0]
	v_pk_mul_f32 v[150:151], v[126:127], v[130:131] op_sel_hi:[1,0]
	v_pk_mul_f32 v[156:157], v[118:119], v[130:131] op_sel_hi:[1,0]
	v_pk_mul_f32 v[158:159], v[116:117], v[130:131] op_sel_hi:[1,0]
	v_pk_mul_f32 v[152:153], v[114:115], v[130:131] op_sel_hi:[1,0]
	v_pk_mul_f32 v[154:155], v[112:113], v[130:131] op_sel_hi:[1,0]
	v_pk_mul_f32 v[130:131], v[164:165], v[164:165]
	v_pk_mul_f32 v[142:143], v[162:163], v[162:163]
	v_lshl_add_u64 v[112:113], s[20:21], 0, v[144:145]
	v_pk_mov_b32 v[174:175], v[142:143], v[130:131] op_sel:[1,0]
	v_mov_b32_e32 v143, v131
	v_pk_add_f32 v[130:131], v[174:175], v[142:143]
	v_pk_mul_f32 v[142:143], v[150:151], v[150:151]
	v_pk_add_f32 v[130:131], v[130:131], v[130:131] op_sel_hi:[0,1]
	v_pk_mul_f32 v[174:175], v[148:149], v[148:149]
	v_mul_f32_e32 v130, v158, v158
	v_pk_mov_b32 v[176:177], v[174:175], v[142:143] op_sel:[1,0]
	v_mov_b32_e32 v175, v143
	v_pk_add_f32 v[142:143], v[176:177], v[174:175]
	v_pk_fma_f32 v[174:175], v[158:159], v[158:159], v[130:131] op_sel_hi:[1,1,0]
	v_mul_f32_e32 v130, v156, v156
	v_pk_add_f32 v[142:143], v[142:143], v[142:143] op_sel_hi:[0,1]
	v_pk_fma_f32 v[176:177], v[156:157], v[156:157], v[130:131] op_sel_hi:[1,1,0]
	v_mul_f32_e32 v174, v154, v154
	v_mul_f32_e32 v176, v155, v155
	v_mul_f32_e32 v130, v152, v152
	v_mul_f32_e32 v142, v153, v153
	v_pk_add_f32 v[174:175], v[174:175], v[176:177]
	v_pk_add_f32 v[130:131], v[130:131], v[142:143]
	v_lshl_add_u64 v[142:143], s[4:5], 0, v[144:145]
	v_pk_add_f32 v[130:131], v[174:175], v[130:131]
	v_readlane_b32 s4, v252, 1
	v_add_f32_e32 v129, v130, v131
	ds_bpermute_b32 v130, v170, v129
	v_readlane_b32 s5, v252, 2
	v_lshl_add_u64 v[174:175], v[142:143], 0, v[188:189]
	flat_load_dwordx4 v[124:127], v[112:113]
	flat_load_dwordx4 v[120:123], v[112:113] offset:64
	flat_load_dwordx4 v[116:119], v[112:113] offset:128
	s_nop 0
	flat_load_dwordx4 v[112:115], v[112:113] offset:192
	s_waitcnt lgkmcnt(0)
	v_add_f32_e32 v129, v129, v130
	ds_bpermute_b32 v130, v171, v129
	global_load_dwordx4 v[174:177], v[174:175], off
	s_waitcnt lgkmcnt(0)
	v_add_f32_e32 v129, v129, v130
	v_fmamk_f32 v129, v129, 0x3c800000, v209
	v_cmp_gt_f32_e64 s[38:39], s0, v129
	v_mul_f32_e32 v130, 0x4b800000, v129
	s_nop 0
	v_cndmask_b32_e64 v129, v129, v130, s[38:39]
	v_rsq_f32_e32 v129, v129
	s_nop 0
	v_mul_f32_e32 v130, 0x45800000, v129
	v_cndmask_b32_e64 v160, v129, v130, s[38:39]
	v_lshl_add_u64 v[130:131], s[4:5], 0, v[144:145]
	v_lshl_add_u64 v[178:179], v[130:131], 0, v[188:189]
	global_load_dwordx4 v[178:181], v[178:179], off
	v_pk_mul_f32 v[148:149], v[148:149], v[160:161] op_sel_hi:[1,0]
	v_pk_mul_f32 v[162:163], v[162:163], v[160:161] op_sel_hi:[1,0]
	v_pk_mul_f32 v[164:165], v[164:165], v[160:161] op_sel_hi:[1,0]
	v_pk_mul_f32 v[156:157], v[156:157], v[160:161] op_sel_hi:[1,0]
	v_pk_mul_f32 v[158:159], v[158:159], v[160:161] op_sel_hi:[1,0]
	s_movk_i32 s4, 0x1f8
	s_movk_i32 s5, 0x1400
	s_waitcnt vmcnt(0)
	v_pk_mul_f32 v[162:163], v[124:125], v[162:163]
	v_pk_mul_f32 v[120:121], v[120:121], v[148:149]
	v_pk_mul_f32 v[124:125], v[150:151], v[160:161] op_sel_hi:[1,0]
	v_pk_mul_f32 v[126:127], v[126:127], v[164:165]
	v_pk_mul_f32 v[122:123], v[122:123], v[124:125]
	v_pk_mul_f32 v[156:157], v[118:119], v[156:157]
	v_pk_mul_f32 v[118:119], v[152:153], v[160:161] op_sel_hi:[1,0]
	v_pk_mul_f32 v[152:153], v[154:155], v[160:161] op_sel_hi:[1,0]
	v_pk_mul_f32 v[116:117], v[116:117], v[158:159]
	v_pk_mul_f32 v[112:113], v[112:113], v[152:153]
	v_pk_mul_f32 v[114:115], v[114:115], v[118:119]
	v_pk_mul_f32 v[148:149], v[178:179], v[120:121]
	v_pk_mul_f32 v[120:121], v[174:175], v[120:121]
	v_pk_mul_f32 v[124:125], v[180:181], v[122:123]
	v_pk_fma_f32 v[120:121], v[178:179], v[162:163], v[120:121]
	v_pk_mul_f32 v[122:123], v[176:177], v[122:123]
	v_pk_mul_f32 v[150:151], v[128:129], v[120:121] op_sel_hi:[0,1]
	v_lshlrev_b32_e32 v120, 4, v172
	v_and_b32_e32 v188, 0x3f0, v120
	v_pk_fma_f32 v[122:123], v[180:181], v[126:127], v[122:123]
	v_lshlrev_b32_e32 v120, 2, v188
	v_mov_b32_e32 v121, v189
	v_pk_fma_f32 v[124:125], v[176:177], v[126:127], v[124:125] neg_lo:[0,0,1] neg_hi:[0,0,1]
	v_pk_mul_f32 v[126:127], v[128:129], v[122:123] op_sel_hi:[0,1]
	v_lshl_add_u64 v[122:123], v[142:143], 0, v[120:121]
	v_lshl_add_u64 v[120:121], v[130:131], 0, v[120:121]
	v_pk_fma_f32 v[148:149], v[174:175], v[162:163], v[148:149] neg_lo:[0,0,1] neg_hi:[0,0,1]
	global_load_dwordx4 v[162:165], v[122:123], off
	global_load_dwordx4 v[172:175], v[120:121], off
	v_pk_mul_f32 v[124:125], v[128:129], v[124:125] op_sel_hi:[0,1]
	v_pk_mul_f32 v[148:149], v[128:129], v[148:149] op_sel_hi:[0,1]
	v_cvt_pk_bf16_f32 v148, v148, v149
	v_cvt_pk_bf16_f32 v149, v124, v125
	v_cvt_pk_bf16_f32 v150, v150, v151
	v_cvt_pk_bf16_f32 v151, v126, v127
	s_waitcnt vmcnt(0)
	v_pk_mul_f32 v[152:153], v[172:173], v[112:113]
	v_pk_mul_f32 v[112:113], v[162:163], v[112:113]
	v_pk_mul_f32 v[118:119], v[174:175], v[114:115]
	v_pk_mul_f32 v[114:115], v[164:165], v[114:115]
	v_pk_fma_f32 v[112:113], v[172:173], v[116:117], v[112:113]
	v_pk_fma_f32 v[118:119], v[164:165], v[156:157], v[118:119] neg_lo:[0,0,1] neg_hi:[0,0,1]
	v_pk_fma_f32 v[114:115], v[174:175], v[156:157], v[114:115]
	v_pk_mul_f32 v[156:157], v[128:129], v[112:113] op_sel_hi:[0,1]
	v_and_or_b32 v112, v161, -4, s48
	v_ashrrev_i32_e32 v113, 31, v112
	v_lshlrev_b64 v[158:159], 9, v[112:113]
	v_lshrrev_b32_e32 v112, 3, v140
	v_pk_fma_f32 v[152:153], v[162:163], v[116:117], v[152:153] neg_lo:[0,0,1] neg_hi:[0,0,1]
	v_and_or_b32 v158, v112, s4, v158
	v_mov_b64_e32 v[112:113], s[90:91]
	v_pk_mul_f32 v[154:155], v[128:129], v[152:153] op_sel_hi:[0,1]
	v_pk_mul_f32 v[152:153], v[128:129], v[114:115] op_sel_hi:[0,1]
	v_mad_i64_i32 v[114:115], s[20:21], v140, s5, v[112:113]
	v_lshl_add_u64 v[114:115], v[114:115], 0, s[58:59]
	v_lshl_add_u64 v[116:117], v[114:115], 0, s[28:29]
	v_lshlrev_b64 v[114:115], 1, v[146:147]
	v_lshl_add_u64 v[160:161], v[116:117], 0, v[114:115]
	v_ashrrev_i32_e32 v116, 3, v146
	v_ashrrev_i32_e32 v117, 31, v116
	v_lshl_add_u64 v[124:125], v[158:159], 0, v[116:117]
	v_lshlrev_b64 v[124:125], 10, v[124:125]
	v_lshl_add_u64 v[124:125], s[92:93], 0, v[124:125]
	v_lshl_add_u64 v[124:125], v[124:125], 0, v[188:189]
	v_pk_mul_f32 v[118:119], v[128:129], v[118:119] op_sel_hi:[0,1]
	v_permlane16_swap_b32_e32 v148, v150
	v_permlane16_swap_b32_e32 v149, v151
	v_cndmask_b32_e32 v125, v161, v125, vcc
	v_cndmask_b32_e32 v124, v160, v124, vcc
	global_store_dwordx4 v[124:125], v[148:151], off
	v_cvt_pk_bf16_f32 v124, v154, v155
	v_cvt_pk_bf16_f32 v125, v118, v119
	v_add_u32_e32 v118, 32, v146
	v_ashrrev_i32_e32 v118, 3, v118
	v_ashrrev_i32_e32 v119, 31, v118
	v_lshl_add_u64 v[148:149], v[158:159], 0, v[118:119]
	v_lshlrev_b64 v[148:149], 10, v[148:149]
	v_lshl_add_u64 v[148:149], s[92:93], 0, v[148:149]
	v_cvt_pk_bf16_f32 v126, v156, v157
	v_cvt_pk_bf16_f32 v127, v152, v153
	v_lshl_add_u64 v[146:147], v[160:161], 0, 64
	v_lshl_add_u64 v[148:149], v[148:149], 0, v[188:189]
	v_permlane16_swap_b32_e32 v124, v126
	v_permlane16_swap_b32_e32 v125, v127
	v_cndmask_b32_e32 v147, v147, v149, vcc
	v_cndmask_b32_e32 v146, v146, v148, vcc
	global_store_dwordx4 v[146:147], v[124:127], off
	s_mov_b64 s[20:21], s[40:41]
	s_nop 0
	v_add_u32_e32 v124, 16, v140
	v_ashrrev_i32_e32 v125, 31, v124
	v_lshlrev_b64 v[126:127], 6, v[124:125]
	v_lshl_add_u64 v[126:127], s[96:97], 0, v[126:127]
	v_lshl_add_u64 v[126:127], v[126:127], 0, v[144:145]
	v_mov_b32_e32 v146, v216
	v_mov_b32_e32 v147, v217
	v_mov_b32_e32 v148, v218
	v_mov_b32_e32 v149, v219
	v_mov_b32_e32 v126, v147
	v_mov_b32_e32 v127, v148
	v_mov_b32_e32 v147, v149
	v_pk_add_f32 v[126:127], v[126:127], v[146:147]
	s_nop 0
	v_add_f32_e32 v125, v126, v127
	ds_bpermute_b32 v126, v170, v125
	s_waitcnt lgkmcnt(0)
	v_add_f32_e32 v125, v125, v126
	ds_bpermute_b32 v126, v171, v125
	s_waitcnt lgkmcnt(0)
	v_add_f32_e32 v125, v125, v126
	v_fmamk_f32 v125, v125, 0x3a800000, v209
	v_cmp_gt_f32_e64 s[38:39], s0, v125
	v_mul_f32_e32 v126, 0x4b800000, v125
	s_nop 0
	v_cndmask_b32_e64 v125, v125, v126, s[38:39]
	v_rsq_f32_e32 v125, v125
	s_nop 0
	v_mul_f32_e32 v126, 0x45800000, v125
	v_cndmask_b32_e64 v146, v125, v126, s[38:39]
	v_pk_mul_f32 v[158:159], v[108:109], v[146:147] op_sel_hi:[1,0]
	v_pk_mul_f32 v[160:161], v[110:111], v[146:147] op_sel_hi:[1,0]
	v_pk_mul_f32 v[162:163], v[158:159], v[158:159]
	v_pk_mul_f32 v[152:153], v[160:161], v[160:161]
	v_pk_mul_f32 v[154:155], v[104:105], v[146:147] op_sel_hi:[1,0]
	v_pk_mov_b32 v[164:165], v[162:163], v[152:153] op_sel:[1,0]
	v_mov_b32_e32 v163, v153
	v_pk_mul_f32 v[156:157], v[106:107], v[146:147] op_sel_hi:[1,0]
	v_pk_add_f32 v[152:153], v[164:165], v[162:163]
	v_pk_mul_f32 v[150:151], v[100:101], v[146:147] op_sel_hi:[1,0]
	v_pk_add_f32 v[152:153], v[152:153], v[152:153] op_sel_hi:[0,1]
	v_pk_mul_f32 v[162:163], v[156:157], v[156:157]
	v_pk_mul_f32 v[164:165], v[154:155], v[154:155]
	v_pk_mul_f32 v[148:149], v[102:103], v[146:147] op_sel_hi:[1,0]
	v_pk_mov_b32 v[172:173], v[164:165], v[162:163] op_sel:[1,0]
	v_mov_b32_e32 v165, v163
	v_mul_f32_e32 v152, v150, v150
	v_pk_add_f32 v[162:163], v[172:173], v[164:165]
	v_pk_fma_f32 v[164:165], v[150:151], v[150:151], v[152:153] op_sel_hi:[1,1,0]
	v_mul_f32_e32 v152, v148, v148
	v_pk_mul_f32 v[126:127], v[98:99], v[146:147] op_sel_hi:[1,0]
	v_pk_mul_f32 v[146:147], v[96:97], v[146:147] op_sel_hi:[1,0]
	v_pk_add_f32 v[162:163], v[162:163], v[162:163] op_sel_hi:[0,1]
	v_pk_fma_f32 v[172:173], v[148:149], v[148:149], v[152:153] op_sel_hi:[1,1,0]
	v_mul_f32_e32 v164, v146, v146
	v_mul_f32_e32 v172, v147, v147
	v_mul_f32_e32 v152, v126, v126
	v_mul_f32_e32 v162, v127, v127
	v_pk_add_f32 v[164:165], v[164:165], v[172:173]
	v_pk_add_f32 v[152:153], v[152:153], v[162:163]
	v_and_b32_e32 v162, 0xfc0, v124
	v_mov_b32_e32 v163, v189
	v_lshl_add_u64 v[96:97], s[20:21], 0, v[144:145]
	v_pk_add_f32 v[152:153], v[164:165], v[152:153]
	v_lshl_add_u64 v[164:165], v[142:143], 0, v[162:163]
	v_lshl_add_u64 v[162:163], v[130:131], 0, v[162:163]
	flat_load_dwordx4 v[108:111], v[96:97]
	flat_load_dwordx4 v[104:107], v[96:97] offset:64
	flat_load_dwordx4 v[100:103], v[96:97] offset:128
	s_nop 0
	flat_load_dwordx4 v[96:99], v[96:97] offset:192
	v_add_f32_e32 v125, v152, v153
	global_load_dwordx4 v[172:175], v[164:165], off
	ds_bpermute_b32 v129, v170, v125
	global_load_dwordx4 v[162:165], v[162:163], off
	s_waitcnt lgkmcnt(0)
	v_add_f32_e32 v125, v125, v129
	ds_bpermute_b32 v129, v171, v125
	s_waitcnt lgkmcnt(0)
	v_add_f32_e32 v125, v125, v129
	v_fmamk_f32 v125, v125, 0x3c800000, v209
	v_cmp_gt_f32_e64 s[38:39], s0, v125
	v_mul_f32_e32 v129, 0x4b800000, v125
	s_nop 0
	v_cndmask_b32_e64 v125, v125, v129, s[38:39]
	v_rsq_f32_e32 v125, v125
	s_nop 0
	v_mul_f32_e32 v129, 0x45800000, v125
	v_cndmask_b32_e64 v152, v125, v129, s[38:39]
	v_pk_mul_f32 v[154:155], v[154:155], v[152:153] op_sel_hi:[1,0]
	v_pk_mul_f32 v[158:159], v[158:159], v[152:153] op_sel_hi:[1,0]
	v_pk_mul_f32 v[156:157], v[156:157], v[152:153] op_sel_hi:[1,0]
	v_pk_mul_f32 v[160:161], v[160:161], v[152:153] op_sel_hi:[1,0]
	v_pk_mul_f32 v[146:147], v[146:147], v[152:153] op_sel_hi:[1,0]
	v_pk_mul_f32 v[150:151], v[150:151], v[152:153] op_sel_hi:[1,0]
	v_pk_mul_f32 v[126:127], v[126:127], v[152:153] op_sel_hi:[1,0]
	v_pk_mul_f32 v[148:149], v[148:149], v[152:153] op_sel_hi:[1,0]
	s_waitcnt vmcnt(0)
	v_pk_mul_f32 v[108:109], v[108:109], v[158:159]
	v_pk_mul_f32 v[104:105], v[104:105], v[154:155]
	v_pk_mul_f32 v[106:107], v[106:107], v[156:157]
	v_pk_mul_f32 v[110:111], v[110:111], v[160:161]
	v_pk_mul_f32 v[96:97], v[96:97], v[146:147]
	v_pk_mul_f32 v[100:101], v[100:101], v[150:151]
	v_pk_mul_f32 v[98:99], v[98:99], v[126:127]
	v_pk_mul_f32 v[156:157], v[162:163], v[104:105]
	v_pk_mul_f32 v[104:105], v[172:173], v[104:105]
	v_pk_mul_f32 v[154:155], v[164:165], v[106:107]
	v_pk_fma_f32 v[104:105], v[162:163], v[108:109], v[104:105]
	v_pk_fma_f32 v[154:155], v[174:175], v[110:111], v[154:155] neg_lo:[0,0,1] neg_hi:[0,0,1]
	v_pk_mul_f32 v[162:163], v[128:129], v[104:105] op_sel_hi:[0,1]
	v_lshlrev_b32_e32 v104, 4, v124
	v_pk_fma_f32 v[158:159], v[172:173], v[108:109], v[156:157] neg_lo:[0,0,1] neg_hi:[0,0,1]
	v_pk_mul_f32 v[156:157], v[128:129], v[154:155] op_sel_hi:[0,1]
	v_and_b32_e32 v154, 0x3f0, v104
	v_pk_mul_f32 v[106:107], v[174:175], v[106:107]
	v_lshlrev_b32_e32 v108, 2, v154
	v_mov_b32_e32 v109, v189
	v_pk_fma_f32 v[106:107], v[164:165], v[110:111], v[106:107]
	v_lshl_add_u64 v[104:105], v[142:143], 0, v[108:109]
	v_lshl_add_u64 v[108:109], v[130:131], 0, v[108:109]
	v_pk_mul_f32 v[160:161], v[128:129], v[158:159] op_sel_hi:[0,1]
	v_pk_mul_f32 v[158:159], v[128:129], v[106:107] op_sel_hi:[0,1]
	global_load_dwordx4 v[104:107], v[104:105], off
	v_pk_mul_f32 v[102:103], v[102:103], v[148:149]
	global_load_dwordx4 v[108:111], v[108:109], off
	v_mov_b32_e32 v155, v189
	s_waitcnt vmcnt(0)
	v_pk_mul_f32 v[146:147], v[108:109], v[96:97]
	v_pk_mul_f32 v[96:97], v[104:105], v[96:97]
	v_pk_mul_f32 v[126:127], v[110:111], v[98:99]
	v_pk_mul_f32 v[98:99], v[106:107], v[98:99]
	v_pk_fma_f32 v[96:97], v[108:109], v[100:101], v[96:97]
	v_pk_fma_f32 v[126:127], v[106:107], v[102:103], v[126:127] neg_lo:[0,0,1] neg_hi:[0,0,1]
	v_pk_fma_f32 v[98:99], v[110:111], v[102:103], v[98:99]
	v_pk_mul_f32 v[102:103], v[128:129], v[96:97] op_sel_hi:[0,1]
	v_ashrrev_i32_e32 v96, 10, v124
	v_and_or_b32 v96, v96, -4, s48
	v_ashrrev_i32_e32 v97, 31, v96
	v_pk_fma_f32 v[146:147], v[104:105], v[100:101], v[146:147] neg_lo:[0,0,1] neg_hi:[0,0,1]
	v_lshlrev_b64 v[104:105], 9, v[96:97]
	v_lshrrev_b32_e32 v96, 3, v124
	v_and_or_b32 v104, v96, s4, v104
	v_mad_i64_i32 v[106:107], s[20:21], v124, s5, v[112:113]
	v_lshl_add_u64 v[108:109], v[104:105], 0, v[116:117]
	v_lshl_add_u64 v[106:107], v[106:107], 0, s[58:59]
	v_lshlrev_b64 v[108:109], 10, v[108:109]
	v_lshl_add_u64 v[106:107], v[106:107], 0, s[28:29]
	v_lshl_add_u64 v[108:109], s[92:93], 0, v[108:109]
	v_pk_mul_f32 v[100:101], v[128:129], v[98:99] op_sel_hi:[0,1]
	v_cvt_pk_bf16_f32 v96, v160, v161
	v_cvt_pk_bf16_f32 v97, v156, v157
	v_cvt_pk_bf16_f32 v98, v162, v163
	v_cvt_pk_bf16_f32 v99, v158, v159
	v_lshl_add_u64 v[106:107], v[106:107], 0, v[114:115]
	v_lshl_add_u64 v[108:109], v[108:109], 0, v[154:155]
	v_permlane16_swap_b32_e32 v96, v98
	v_permlane16_swap_b32_e32 v97, v99
	v_cndmask_b32_e32 v109, v107, v109, vcc
	v_cndmask_b32_e32 v108, v106, v108, vcc
	v_pk_mul_f32 v[126:127], v[128:129], v[126:127] op_sel_hi:[0,1]
	v_pk_mul_f32 v[146:147], v[128:129], v[146:147] op_sel_hi:[0,1]
	global_store_dwordx4 v[108:109], v[96:99], off
	s_mov_b64 s[20:21], s[40:41]
	s_nop 0
	v_cvt_pk_bf16_f32 v96, v146, v147
	v_cvt_pk_bf16_f32 v97, v126, v127
	v_cvt_pk_bf16_f32 v98, v102, v103
	v_lshl_add_u64 v[102:103], v[104:105], 0, v[118:119]
	v_lshlrev_b64 v[102:103], 10, v[102:103]
	v_lshl_add_u64 v[102:103], s[92:93], 0, v[102:103]
	v_cvt_pk_bf16_f32 v99, v100, v101
	v_lshl_add_u64 v[100:101], v[106:107], 0, 64
	v_lshl_add_u64 v[102:103], v[102:103], 0, v[154:155]
	v_permlane16_swap_b32_e32 v96, v98
	v_permlane16_swap_b32_e32 v97, v99
	v_cndmask_b32_e32 v101, v101, v103, vcc
	v_cndmask_b32_e32 v100, v100, v102, vcc
	global_store_dwordx4 v[100:101], v[96:99], off
	s_nop 1
	v_add_u32_e32 v96, 32, v140
	v_ashrrev_i32_e32 v97, 31, v96
	v_lshlrev_b64 v[98:99], 6, v[96:97]
	v_lshl_add_u64 v[98:99], s[96:97], 0, v[98:99]
	v_lshl_add_u64 v[98:99], v[98:99], 0, v[144:145]
	v_mov_b32_e32 v98, v220
	v_mov_b32_e32 v99, v221
	v_mov_b32_e32 v100, v222
	v_mov_b32_e32 v101, v223
	v_mov_b32_e32 v102, v99
	v_mov_b32_e32 v103, v100
	v_mov_b32_e32 v99, v101
	v_pk_add_f32 v[98:99], v[102:103], v[98:99]
	s_nop 0
	v_add_f32_e32 v97, v98, v99
	ds_bpermute_b32 v98, v170, v97
	s_waitcnt lgkmcnt(0)
	v_add_f32_e32 v97, v97, v98
	ds_bpermute_b32 v98, v171, v97
	s_waitcnt lgkmcnt(0)
	v_add_f32_e32 v97, v97, v98
	v_fmamk_f32 v97, v97, 0x3a800000, v209
	v_cmp_gt_f32_e64 s[38:39], s0, v97
	v_mul_f32_e32 v98, 0x4b800000, v97
	s_nop 0
	v_cndmask_b32_e64 v97, v97, v98, s[38:39]
	v_rsq_f32_e32 v97, v97
	s_nop 0
	v_mul_f32_e32 v98, 0x45800000, v97
	v_cndmask_b32_e64 v100, v97, v98, s[38:39]
	v_pk_mul_f32 v[124:125], v[92:93], v[100:101] op_sel_hi:[1,0]
	v_pk_mul_f32 v[126:127], v[94:95], v[100:101] op_sel_hi:[1,0]
	v_pk_mul_f32 v[146:147], v[124:125], v[124:125]
	v_pk_mul_f32 v[106:107], v[126:127], v[126:127]
	v_pk_mul_f32 v[108:109], v[88:89], v[100:101] op_sel_hi:[1,0]
	v_pk_mov_b32 v[148:149], v[146:147], v[106:107] op_sel:[1,0]
	v_mov_b32_e32 v147, v107
	v_pk_mul_f32 v[110:111], v[90:91], v[100:101] op_sel_hi:[1,0]
	v_pk_add_f32 v[106:107], v[148:149], v[146:147]
	v_pk_mul_f32 v[104:105], v[84:85], v[100:101] op_sel_hi:[1,0]
	v_pk_add_f32 v[106:107], v[106:107], v[106:107] op_sel_hi:[0,1]
	v_pk_mul_f32 v[146:147], v[110:111], v[110:111]
	v_pk_mul_f32 v[148:149], v[108:109], v[108:109]
	v_pk_mul_f32 v[102:103], v[86:87], v[100:101] op_sel_hi:[1,0]
	v_pk_mov_b32 v[150:151], v[148:149], v[146:147] op_sel:[1,0]
	v_mov_b32_e32 v149, v147
	v_mul_f32_e32 v106, v104, v104
	v_pk_add_f32 v[146:147], v[150:151], v[148:149]
	v_pk_fma_f32 v[148:149], v[104:105], v[104:105], v[106:107] op_sel_hi:[1,1,0]
	v_mul_f32_e32 v106, v102, v102
	v_pk_mul_f32 v[98:99], v[82:83], v[100:101] op_sel_hi:[1,0]
	v_pk_mul_f32 v[100:101], v[80:81], v[100:101] op_sel_hi:[1,0]
	v_pk_add_f32 v[146:147], v[146:147], v[146:147] op_sel_hi:[0,1]
	v_pk_fma_f32 v[150:151], v[102:103], v[102:103], v[106:107] op_sel_hi:[1,1,0]
	v_mul_f32_e32 v148, v100, v100
	v_mul_f32_e32 v150, v101, v101
	v_mul_f32_e32 v106, v98, v98
	v_mul_f32_e32 v146, v99, v99
	v_pk_add_f32 v[148:149], v[148:149], v[150:151]
	v_pk_add_f32 v[106:107], v[106:107], v[146:147]
	v_and_b32_e32 v146, 0xfc0, v96
	v_mov_b32_e32 v147, v189
	v_lshl_add_u64 v[80:81], s[20:21], 0, v[144:145]
	v_pk_add_f32 v[106:107], v[148:149], v[106:107]
	v_lshl_add_u64 v[148:149], v[142:143], 0, v[146:147]
	v_lshl_add_u64 v[146:147], v[130:131], 0, v[146:147]
	flat_load_dwordx4 v[92:95], v[80:81]
	flat_load_dwordx4 v[88:91], v[80:81] offset:64
	flat_load_dwordx4 v[84:87], v[80:81] offset:128
	s_nop 0
	flat_load_dwordx4 v[80:83], v[80:81] offset:192
	v_add_f32_e32 v97, v106, v107
	global_load_dwordx4 v[148:151], v[148:149], off
	ds_bpermute_b32 v106, v170, v97
	global_load_dwordx4 v[152:155], v[146:147], off
	v_mov_b32_e32 v147, v189
	s_waitcnt lgkmcnt(0)
	v_add_f32_e32 v97, v97, v106
	ds_bpermute_b32 v106, v171, v97
	s_waitcnt lgkmcnt(0)
	v_add_f32_e32 v97, v97, v106
	v_fmamk_f32 v97, v97, 0x3c800000, v209
	v_cmp_gt_f32_e64 s[38:39], s0, v97
	v_mul_f32_e32 v106, 0x4b800000, v97
	s_nop 0
	v_cndmask_b32_e64 v97, v97, v106, s[38:39]
	v_rsq_f32_e32 v97, v97
	s_nop 0
	v_mul_f32_e32 v106, 0x45800000, v97
	v_cndmask_b32_e64 v106, v97, v106, s[38:39]
	v_pk_mul_f32 v[108:109], v[108:109], v[106:107] op_sel_hi:[1,0]
	v_pk_mul_f32 v[124:125], v[124:125], v[106:107] op_sel_hi:[1,0]
	v_pk_mul_f32 v[110:111], v[110:111], v[106:107] op_sel_hi:[1,0]
	v_pk_mul_f32 v[126:127], v[126:127], v[106:107] op_sel_hi:[1,0]
	v_pk_mul_f32 v[100:101], v[100:101], v[106:107] op_sel_hi:[1,0]
	v_pk_mul_f32 v[104:105], v[104:105], v[106:107] op_sel_hi:[1,0]
	v_pk_mul_f32 v[98:99], v[98:99], v[106:107] op_sel_hi:[1,0]
	v_pk_mul_f32 v[102:103], v[102:103], v[106:107] op_sel_hi:[1,0]
	s_waitcnt vmcnt(0)
	v_pk_mul_f32 v[92:93], v[92:93], v[124:125]
	v_pk_mul_f32 v[88:89], v[88:89], v[108:109]
	v_pk_mul_f32 v[90:91], v[90:91], v[110:111]
	v_pk_mul_f32 v[94:95], v[94:95], v[126:127]
	v_pk_mul_f32 v[80:81], v[80:81], v[100:101]
	v_pk_mul_f32 v[84:85], v[84:85], v[104:105]
	v_pk_mul_f32 v[82:83], v[82:83], v[98:99]
	v_pk_mul_f32 v[110:111], v[152:153], v[88:89]
	v_pk_mul_f32 v[88:89], v[148:149], v[88:89]
	v_pk_mul_f32 v[108:109], v[154:155], v[90:91]
	v_pk_fma_f32 v[88:89], v[152:153], v[92:93], v[88:89]
	v_pk_fma_f32 v[110:111], v[148:149], v[92:93], v[110:111] neg_lo:[0,0,1] neg_hi:[0,0,1]
	v_pk_mul_f32 v[126:127], v[128:129], v[88:89] op_sel_hi:[0,1]
	v_lshlrev_b32_e32 v88, 4, v96
	v_and_b32_e32 v146, 0x3f0, v88
	v_pk_mul_f32 v[90:91], v[150:151], v[90:91]
	v_lshlrev_b32_e32 v92, 2, v146
	v_mov_b32_e32 v93, v189
	v_pk_fma_f32 v[90:91], v[154:155], v[94:95], v[90:91]
	v_lshl_add_u64 v[88:89], v[142:143], 0, v[92:93]
	v_lshl_add_u64 v[92:93], v[130:131], 0, v[92:93]
	v_pk_fma_f32 v[108:109], v[150:151], v[94:95], v[108:109] neg_lo:[0,0,1] neg_hi:[0,0,1]
	v_pk_mul_f32 v[124:125], v[128:129], v[110:111] op_sel_hi:[0,1]
	v_pk_mul_f32 v[110:111], v[128:129], v[90:91] op_sel_hi:[0,1]
	global_load_dwordx4 v[88:91], v[88:89], off
	v_pk_mul_f32 v[86:87], v[86:87], v[102:103]
	global_load_dwordx4 v[92:95], v[92:93], off
	v_pk_mul_f32 v[108:109], v[128:129], v[108:109] op_sel_hi:[0,1]
	s_waitcnt vmcnt(0)
	v_pk_mul_f32 v[100:101], v[92:93], v[80:81]
	v_pk_mul_f32 v[80:81], v[88:89], v[80:81]
	v_pk_mul_f32 v[98:99], v[94:95], v[82:83]
	v_pk_mul_f32 v[82:83], v[90:91], v[82:83]
	v_pk_fma_f32 v[80:81], v[92:93], v[84:85], v[80:81]
	v_pk_fma_f32 v[98:99], v[90:91], v[86:87], v[98:99] neg_lo:[0,0,1] neg_hi:[0,0,1]
	v_pk_fma_f32 v[82:83], v[94:95], v[86:87], v[82:83]
	v_pk_mul_f32 v[86:87], v[128:129], v[80:81] op_sel_hi:[0,1]
	v_ashrrev_i32_e32 v80, 10, v96
	v_and_or_b32 v80, v80, -4, s48
	v_ashrrev_i32_e32 v81, 31, v80
	v_pk_fma_f32 v[100:101], v[88:89], v[84:85], v[100:101] neg_lo:[0,0,1] neg_hi:[0,0,1]
	v_lshlrev_b64 v[88:89], 9, v[80:81]
	v_lshrrev_b32_e32 v80, 3, v96
	v_and_or_b32 v88, v80, s4, v88
	v_mad_i64_i32 v[90:91], s[20:21], v96, s5, v[112:113]
	v_lshl_add_u64 v[92:93], v[88:89], 0, v[116:117]
	v_lshl_add_u64 v[90:91], v[90:91], 0, s[58:59]
	v_lshlrev_b64 v[92:93], 10, v[92:93]
	v_lshl_add_u64 v[90:91], v[90:91], 0, s[28:29]
	v_lshl_add_u64 v[92:93], s[92:93], 0, v[92:93]
	v_pk_mul_f32 v[84:85], v[128:129], v[82:83] op_sel_hi:[0,1]
	v_cvt_pk_bf16_f32 v80, v124, v125
	v_cvt_pk_bf16_f32 v81, v108, v109
	v_cvt_pk_bf16_f32 v82, v126, v127
	v_cvt_pk_bf16_f32 v83, v110, v111
	v_lshl_add_u64 v[90:91], v[90:91], 0, v[114:115]
	v_lshl_add_u64 v[92:93], v[92:93], 0, v[146:147]
	v_permlane16_swap_b32_e32 v80, v82
	v_permlane16_swap_b32_e32 v81, v83
	v_cndmask_b32_e32 v93, v91, v93, vcc
	v_cndmask_b32_e32 v92, v90, v92, vcc
	v_pk_mul_f32 v[98:99], v[128:129], v[98:99] op_sel_hi:[0,1]
	v_pk_mul_f32 v[100:101], v[128:129], v[100:101] op_sel_hi:[0,1]
	global_store_dwordx4 v[92:93], v[80:83], off
	s_mov_b64 s[20:21], s[40:41]
	s_nop 0
	v_cvt_pk_bf16_f32 v80, v100, v101
	v_cvt_pk_bf16_f32 v81, v98, v99
	v_cvt_pk_bf16_f32 v82, v86, v87
	v_lshl_add_u64 v[86:87], v[88:89], 0, v[118:119]
	v_lshlrev_b64 v[86:87], 10, v[86:87]
	v_lshl_add_u64 v[86:87], s[92:93], 0, v[86:87]
	v_cvt_pk_bf16_f32 v83, v84, v85
	v_lshl_add_u64 v[84:85], v[90:91], 0, 64
	v_lshl_add_u64 v[86:87], v[86:87], 0, v[146:147]
	v_permlane16_swap_b32_e32 v80, v82
	v_permlane16_swap_b32_e32 v81, v83
	v_cndmask_b32_e32 v85, v85, v87, vcc
	v_cndmask_b32_e32 v84, v84, v86, vcc
	global_store_dwordx4 v[84:85], v[80:83], off
	s_nop 1
	v_add_u32_e32 v80, 48, v140
	v_ashrrev_i32_e32 v81, 31, v80
	v_lshlrev_b64 v[82:83], 6, v[80:81]
	v_lshl_add_u64 v[82:83], s[96:97], 0, v[82:83]
	v_lshl_add_u64 v[82:83], v[82:83], 0, v[144:145]
	v_mov_b32_e32 v82, v224
	v_mov_b32_e32 v83, v225
	v_mov_b32_e32 v84, v226
	v_mov_b32_e32 v85, v227
	v_mov_b32_e32 v86, v83
	v_mov_b32_e32 v87, v84
	v_mov_b32_e32 v83, v85
	v_pk_add_f32 v[82:83], v[86:87], v[82:83]
	s_nop 0
	v_add_f32_e32 v81, v82, v83
	ds_bpermute_b32 v82, v170, v81
	s_waitcnt lgkmcnt(0)
	v_add_f32_e32 v81, v81, v82
	ds_bpermute_b32 v82, v171, v81
	s_waitcnt lgkmcnt(0)
	v_add_f32_e32 v81, v81, v82
	v_fmamk_f32 v81, v81, 0x3a800000, v209
	v_cmp_gt_f32_e64 s[38:39], s0, v81
	v_mul_f32_e32 v82, 0x4b800000, v81
	s_nop 0
	v_cndmask_b32_e64 v81, v81, v82, s[38:39]
	v_rsq_f32_e32 v81, v81
	s_nop 0
	v_mul_f32_e32 v82, 0x45800000, v81
	v_cndmask_b32_e64 v84, v81, v82, s[38:39]
	v_pk_mul_f32 v[76:77], v[76:77], v[84:85] op_sel_hi:[1,0]
	v_pk_mul_f32 v[78:79], v[78:79], v[84:85] op_sel_hi:[1,0]
	v_pk_mul_f32 v[100:101], v[76:77], v[76:77]
	v_pk_mul_f32 v[90:91], v[78:79], v[78:79]
	v_pk_mul_f32 v[72:73], v[72:73], v[84:85] op_sel_hi:[1,0]
	v_pk_mov_b32 v[102:103], v[100:101], v[90:91] op_sel:[1,0]
	v_mov_b32_e32 v101, v91
	v_pk_mul_f32 v[74:75], v[74:75], v[84:85] op_sel_hi:[1,0]
	v_pk_add_f32 v[90:91], v[102:103], v[100:101]
	v_pk_mul_f32 v[88:89], v[68:69], v[84:85] op_sel_hi:[1,0]
	v_pk_add_f32 v[90:91], v[90:91], v[90:91] op_sel_hi:[0,1]
	v_pk_mul_f32 v[100:101], v[74:75], v[74:75]
	v_pk_mul_f32 v[102:103], v[72:73], v[72:73]
	v_pk_mul_f32 v[86:87], v[70:71], v[84:85] op_sel_hi:[1,0]
	v_pk_mov_b32 v[104:105], v[102:103], v[100:101] op_sel:[1,0]
	v_mov_b32_e32 v103, v101
	v_mul_f32_e32 v90, v88, v88
	v_pk_add_f32 v[100:101], v[104:105], v[102:103]
	v_pk_fma_f32 v[102:103], v[88:89], v[88:89], v[90:91] op_sel_hi:[1,1,0]
	v_mul_f32_e32 v90, v86, v86
	v_pk_mul_f32 v[82:83], v[66:67], v[84:85] op_sel_hi:[1,0]
	v_pk_mul_f32 v[84:85], v[64:65], v[84:85] op_sel_hi:[1,0]
	v_pk_fma_f32 v[104:105], v[86:87], v[86:87], v[90:91] op_sel_hi:[1,1,0]
	v_pk_add_f32 v[100:101], v[100:101], v[100:101] op_sel_hi:[0,1]
	v_mul_f32_e32 v102, v84, v84
	v_mul_f32_e32 v104, v85, v85
	v_mul_f32_e32 v90, v82, v82
	v_mul_f32_e32 v100, v83, v83
	v_pk_add_f32 v[102:103], v[102:103], v[104:105]
	v_and_b32_e32 v104, 0xfc0, v80
	v_mov_b32_e32 v105, v189
	v_lshl_add_u64 v[64:65], s[20:21], 0, v[144:145]
	v_pk_add_f32 v[90:91], v[90:91], v[100:101]
	v_lshl_add_u64 v[100:101], v[142:143], 0, v[104:105]
	v_lshl_add_u64 v[104:105], v[130:131], 0, v[104:105]
	flat_load_dwordx4 v[92:95], v[64:65]
	flat_load_dwordx4 v[96:99], v[64:65] offset:64
	flat_load_dwordx4 v[68:71], v[64:65] offset:128
	s_nop 0
	flat_load_dwordx4 v[64:67], v[64:65] offset:192
	v_pk_add_f32 v[90:91], v[102:103], v[90:91]
	global_load_dwordx4 v[100:103], v[100:101], off
	v_add_f32_e32 v81, v90, v91
	global_load_dwordx4 v[104:107], v[104:105], off
	ds_bpermute_b32 v90, v170, v81
	s_waitcnt lgkmcnt(0)
	v_add_f32_e32 v81, v81, v90
	ds_bpermute_b32 v90, v171, v81
	s_waitcnt lgkmcnt(0)
	v_add_f32_e32 v81, v81, v90
	v_fmamk_f32 v81, v81, 0x3c800000, v209
	v_cmp_gt_f32_e64 s[38:39], s0, v81
	v_mul_f32_e32 v90, 0x4b800000, v81
	s_nop 0
	v_cndmask_b32_e64 v81, v81, v90, s[38:39]
	v_rsq_f32_e32 v81, v81
	s_nop 0
	v_mul_f32_e32 v90, 0x45800000, v81
	v_cndmask_b32_e64 v90, v81, v90, s[38:39]
	v_pk_mul_f32 v[72:73], v[72:73], v[90:91] op_sel_hi:[1,0]
	v_pk_mul_f32 v[76:77], v[76:77], v[90:91] op_sel_hi:[1,0]
	v_pk_mul_f32 v[78:79], v[78:79], v[90:91] op_sel_hi:[1,0]
	v_pk_mul_f32 v[74:75], v[74:75], v[90:91] op_sel_hi:[1,0]
	v_pk_mul_f32 v[84:85], v[84:85], v[90:91] op_sel_hi:[1,0]
	v_pk_mul_f32 v[88:89], v[88:89], v[90:91] op_sel_hi:[1,0]
	v_pk_mul_f32 v[82:83], v[82:83], v[90:91] op_sel_hi:[1,0]
	v_pk_mul_f32 v[86:87], v[86:87], v[90:91] op_sel_hi:[1,0]
	s_waitcnt vmcnt(0)
	v_pk_mul_f32 v[78:79], v[94:95], v[78:79]
	v_pk_mul_f32 v[72:73], v[96:97], v[72:73]
	v_pk_mul_f32 v[76:77], v[92:93], v[76:77]
	v_pk_mul_f32 v[74:75], v[98:99], v[74:75]
	v_pk_mul_f32 v[64:65], v[64:65], v[84:85]
	v_pk_mul_f32 v[68:69], v[68:69], v[88:89]
	v_pk_mul_f32 v[66:67], v[66:67], v[82:83]
	v_pk_mul_f32 v[94:95], v[104:105], v[72:73]
	v_pk_mul_f32 v[72:73], v[100:101], v[72:73]
	v_pk_fma_f32 v[94:95], v[100:101], v[76:77], v[94:95] neg_lo:[0,0,1] neg_hi:[0,0,1]
	v_pk_fma_f32 v[72:73], v[104:105], v[76:77], v[72:73]
	v_pk_mul_f32 v[92:93], v[106:107], v[74:75]
	v_pk_mul_f32 v[98:99], v[128:129], v[72:73] op_sel_hi:[0,1]
	v_lshlrev_b32_e32 v72, 4, v80
	v_and_b32_e32 v100, 0x3f0, v72
	v_pk_mul_f32 v[74:75], v[102:103], v[74:75]
	v_lshlrev_b32_e32 v76, 2, v100
	v_mov_b32_e32 v77, v189
	v_pk_fma_f32 v[74:75], v[106:107], v[78:79], v[74:75]
	v_lshl_add_u64 v[72:73], v[142:143], 0, v[76:77]
	v_lshl_add_u64 v[76:77], v[130:131], 0, v[76:77]
	v_pk_fma_f32 v[92:93], v[102:103], v[78:79], v[92:93] neg_lo:[0,0,1] neg_hi:[0,0,1]
	v_pk_mul_f32 v[96:97], v[128:129], v[94:95] op_sel_hi:[0,1]
	v_pk_mul_f32 v[94:95], v[128:129], v[74:75] op_sel_hi:[0,1]
	global_load_dwordx4 v[72:75], v[72:73], off
	v_pk_mul_f32 v[70:71], v[70:71], v[86:87]
	global_load_dwordx4 v[76:79], v[76:77], off
	v_mov_b32_e32 v101, v189
	v_pk_mul_f32 v[92:93], v[128:129], v[92:93] op_sel_hi:[0,1]
	s_waitcnt vmcnt(0)
	v_pk_mul_f32 v[84:85], v[76:77], v[64:65]
	v_pk_mul_f32 v[64:65], v[72:73], v[64:65]
	v_pk_mul_f32 v[82:83], v[78:79], v[66:67]
	v_pk_mul_f32 v[66:67], v[74:75], v[66:67]
	v_pk_fma_f32 v[64:65], v[76:77], v[68:69], v[64:65]
	v_pk_fma_f32 v[82:83], v[74:75], v[70:71], v[82:83] neg_lo:[0,0,1] neg_hi:[0,0,1]
	v_pk_fma_f32 v[66:67], v[78:79], v[70:71], v[66:67]
	v_pk_mul_f32 v[70:71], v[128:129], v[64:65] op_sel_hi:[0,1]
	v_ashrrev_i32_e32 v64, 10, v80
	v_and_or_b32 v64, v64, -4, s48
	v_ashrrev_i32_e32 v65, 31, v64
	v_pk_fma_f32 v[84:85], v[72:73], v[68:69], v[84:85] neg_lo:[0,0,1] neg_hi:[0,0,1]
	v_lshlrev_b64 v[72:73], 9, v[64:65]
	v_lshrrev_b32_e32 v64, 3, v80
	v_and_or_b32 v72, v64, s4, v72
	v_mad_i64_i32 v[74:75], s[20:21], v80, s5, v[112:113]
	v_lshl_add_u64 v[76:77], v[72:73], 0, v[116:117]
	v_lshl_add_u64 v[74:75], v[74:75], 0, s[58:59]
	v_lshlrev_b64 v[76:77], 10, v[76:77]
	v_lshl_add_u64 v[74:75], v[74:75], 0, s[28:29]
	v_lshl_add_u64 v[76:77], s[92:93], 0, v[76:77]
	v_pk_mul_f32 v[68:69], v[128:129], v[66:67] op_sel_hi:[0,1]
	v_cvt_pk_bf16_f32 v64, v96, v97
	v_cvt_pk_bf16_f32 v65, v92, v93
	v_cvt_pk_bf16_f32 v66, v98, v99
	v_cvt_pk_bf16_f32 v67, v94, v95
	v_lshl_add_u64 v[74:75], v[74:75], 0, v[114:115]
	v_lshl_add_u64 v[76:77], v[76:77], 0, v[100:101]
	v_permlane16_swap_b32_e32 v64, v66
	v_permlane16_swap_b32_e32 v65, v67
	v_cndmask_b32_e32 v77, v75, v77, vcc
	v_cndmask_b32_e32 v76, v74, v76, vcc
	v_pk_mul_f32 v[82:83], v[128:129], v[82:83] op_sel_hi:[0,1]
	v_pk_mul_f32 v[84:85], v[128:129], v[84:85] op_sel_hi:[0,1]
	global_store_dwordx4 v[76:77], v[64:67], off
	s_mov_b64 s[20:21], s[40:41]
	s_nop 0
	v_cvt_pk_bf16_f32 v64, v84, v85
	v_cvt_pk_bf16_f32 v65, v82, v83
	v_cvt_pk_bf16_f32 v66, v70, v71
	v_lshl_add_u64 v[70:71], v[72:73], 0, v[118:119]
	v_lshlrev_b64 v[70:71], 10, v[70:71]
	v_lshl_add_u64 v[70:71], s[92:93], 0, v[70:71]
	v_cvt_pk_bf16_f32 v67, v68, v69
	v_lshl_add_u64 v[68:69], v[74:75], 0, 64
	v_lshl_add_u64 v[70:71], v[70:71], 0, v[100:101]
	v_permlane16_swap_b32_e32 v64, v66
	v_permlane16_swap_b32_e32 v65, v67
	v_cndmask_b32_e32 v69, v69, v71, vcc
	v_cndmask_b32_e32 v68, v68, v70, vcc
	global_store_dwordx4 v[68:69], v[64:67], off
	s_nop 1
	v_add_u32_e32 v64, 0x80, v140
	v_ashrrev_i32_e32 v65, 31, v64
	v_lshlrev_b64 v[66:67], 6, v[64:65]
	v_lshl_add_u64 v[66:67], s[96:97], 0, v[66:67]
	v_lshl_add_u64 v[66:67], v[66:67], 0, v[144:145]
	v_mov_b32_e32 v66, v228
	v_mov_b32_e32 v67, v229
	v_mov_b32_e32 v68, v230
	v_mov_b32_e32 v69, v231
	v_mov_b32_e32 v70, v67
	v_mov_b32_e32 v71, v68
	v_mov_b32_e32 v67, v69
	v_pk_add_f32 v[66:67], v[70:71], v[66:67]
	s_nop 0
	v_add_f32_e32 v65, v66, v67
	ds_bpermute_b32 v66, v170, v65
	s_waitcnt lgkmcnt(0)
	v_add_f32_e32 v65, v65, v66
	ds_bpermute_b32 v66, v171, v65
	s_waitcnt lgkmcnt(0)
	v_add_f32_e32 v65, v65, v66
	v_fmamk_f32 v65, v65, 0x3a800000, v209
	v_cmp_gt_f32_e64 s[38:39], s0, v65
	v_mul_f32_e32 v66, 0x4b800000, v65
	s_nop 0
	v_cndmask_b32_e64 v65, v65, v66, s[38:39]
	v_rsq_f32_e32 v65, v65
	s_nop 0
	v_mul_f32_e32 v66, 0x45800000, v65
	v_cndmask_b32_e64 v68, v65, v66, s[38:39]
	v_pk_mul_f32 v[60:61], v[60:61], v[68:69] op_sel_hi:[1,0]
	v_pk_mul_f32 v[62:63], v[62:63], v[68:69] op_sel_hi:[1,0]
	v_pk_mul_f32 v[84:85], v[60:61], v[60:61]
	v_pk_mul_f32 v[74:75], v[62:63], v[62:63]
	v_pk_mul_f32 v[56:57], v[56:57], v[68:69] op_sel_hi:[1,0]
	v_pk_mov_b32 v[86:87], v[84:85], v[74:75] op_sel:[1,0]
	v_mov_b32_e32 v85, v75
	v_pk_mul_f32 v[58:59], v[58:59], v[68:69] op_sel_hi:[1,0]
	v_pk_add_f32 v[74:75], v[86:87], v[84:85]
	v_pk_mul_f32 v[72:73], v[52:53], v[68:69] op_sel_hi:[1,0]
	v_pk_add_f32 v[74:75], v[74:75], v[74:75] op_sel_hi:[0,1]
	v_pk_mul_f32 v[84:85], v[58:59], v[58:59]
	v_pk_mul_f32 v[86:87], v[56:57], v[56:57]
	v_pk_mul_f32 v[70:71], v[54:55], v[68:69] op_sel_hi:[1,0]
	v_pk_mov_b32 v[88:89], v[86:87], v[84:85] op_sel:[1,0]
	v_mov_b32_e32 v87, v85
	v_mul_f32_e32 v74, v72, v72
	v_pk_add_f32 v[84:85], v[88:89], v[86:87]
	v_pk_fma_f32 v[86:87], v[72:73], v[72:73], v[74:75] op_sel_hi:[1,1,0]
	v_mul_f32_e32 v74, v70, v70
	v_pk_mul_f32 v[66:67], v[50:51], v[68:69] op_sel_hi:[1,0]
	v_pk_mul_f32 v[68:69], v[48:49], v[68:69] op_sel_hi:[1,0]
	v_pk_fma_f32 v[88:89], v[70:71], v[70:71], v[74:75] op_sel_hi:[1,1,0]
	v_pk_add_f32 v[84:85], v[84:85], v[84:85] op_sel_hi:[0,1]
	v_mul_f32_e32 v86, v68, v68
	v_mul_f32_e32 v88, v69, v69
	v_mul_f32_e32 v74, v66, v66
	v_mul_f32_e32 v84, v67, v67
	v_pk_add_f32 v[86:87], v[86:87], v[88:89]
	v_and_b32_e32 v88, 0xfc0, v64
	v_mov_b32_e32 v89, v189
	v_lshl_add_u64 v[48:49], s[20:21], 0, v[144:145]
	v_pk_add_f32 v[74:75], v[74:75], v[84:85]
	v_lshl_add_u64 v[84:85], v[142:143], 0, v[88:89]
	v_lshl_add_u64 v[88:89], v[130:131], 0, v[88:89]
	flat_load_dwordx4 v[76:79], v[48:49]
	flat_load_dwordx4 v[80:83], v[48:49] offset:64
	flat_load_dwordx4 v[52:55], v[48:49] offset:128
	s_nop 0
	flat_load_dwordx4 v[48:51], v[48:49] offset:192
	v_pk_add_f32 v[74:75], v[86:87], v[74:75]
	global_load_dwordx4 v[84:87], v[84:85], off
	v_add_f32_e32 v65, v74, v75
	global_load_dwordx4 v[88:91], v[88:89], off
	ds_bpermute_b32 v74, v170, v65
	s_waitcnt lgkmcnt(0)
	v_add_f32_e32 v65, v65, v74
	ds_bpermute_b32 v74, v171, v65
	s_waitcnt lgkmcnt(0)
	v_add_f32_e32 v65, v65, v74
	v_fmamk_f32 v65, v65, 0x3c800000, v209
	v_cmp_gt_f32_e64 s[38:39], s0, v65
	v_mul_f32_e32 v74, 0x4b800000, v65
	s_nop 0
	v_cndmask_b32_e64 v65, v65, v74, s[38:39]
	v_rsq_f32_e32 v65, v65
	s_nop 0
	v_mul_f32_e32 v74, 0x45800000, v65
	v_cndmask_b32_e64 v74, v65, v74, s[38:39]
	v_pk_mul_f32 v[58:59], v[58:59], v[74:75] op_sel_hi:[1,0]
	v_pk_mul_f32 v[56:57], v[56:57], v[74:75] op_sel_hi:[1,0]
	v_pk_mul_f32 v[60:61], v[60:61], v[74:75] op_sel_hi:[1,0]
	v_pk_mul_f32 v[62:63], v[62:63], v[74:75] op_sel_hi:[1,0]
	v_pk_mul_f32 v[68:69], v[68:69], v[74:75] op_sel_hi:[1,0]
	v_pk_mul_f32 v[72:73], v[72:73], v[74:75] op_sel_hi:[1,0]
	v_pk_mul_f32 v[66:67], v[66:67], v[74:75] op_sel_hi:[1,0]
	v_pk_mul_f32 v[70:71], v[70:71], v[74:75] op_sel_hi:[1,0]
	s_waitcnt vmcnt(0)
	v_pk_mul_f32 v[62:63], v[78:79], v[62:63]
	v_pk_mul_f32 v[56:57], v[80:81], v[56:57]
	v_pk_mul_f32 v[58:59], v[82:83], v[58:59]
	v_pk_mul_f32 v[60:61], v[76:77], v[60:61]
	v_pk_mul_f32 v[48:49], v[48:49], v[68:69]
	v_pk_mul_f32 v[52:53], v[52:53], v[72:73]
	v_pk_mul_f32 v[50:51], v[50:51], v[66:67]
	v_pk_mul_f32 v[76:77], v[90:91], v[58:59]
	v_pk_mul_f32 v[78:79], v[88:89], v[56:57]
	v_pk_mul_f32 v[58:59], v[86:87], v[58:59]
	v_pk_mul_f32 v[56:57], v[84:85], v[56:57]
	v_pk_fma_f32 v[78:79], v[84:85], v[60:61], v[78:79] neg_lo:[0,0,1] neg_hi:[0,0,1]
	v_pk_fma_f32 v[56:57], v[88:89], v[60:61], v[56:57]
	v_pk_fma_f32 v[58:59], v[90:91], v[62:63], v[58:59]
	v_pk_fma_f32 v[76:77], v[86:87], v[62:63], v[76:77] neg_lo:[0,0,1] neg_hi:[0,0,1]
	v_pk_mul_f32 v[80:81], v[128:129], v[78:79] op_sel_hi:[0,1]
	v_pk_mul_f32 v[78:79], v[128:129], v[58:59] op_sel_hi:[0,1]
	v_pk_mul_f32 v[82:83], v[128:129], v[56:57] op_sel_hi:[0,1]
	global_load_dwordx4 v[56:59], v[122:123], off
	global_load_dwordx4 v[60:63], v[120:121], off
	v_pk_mul_f32 v[54:55], v[54:55], v[70:71]
	v_pk_mul_f32 v[76:77], v[128:129], v[76:77] op_sel_hi:[0,1]
	s_waitcnt vmcnt(0)
	v_pk_mul_f32 v[68:69], v[60:61], v[48:49]
	v_pk_mul_f32 v[48:49], v[56:57], v[48:49]
	v_pk_mul_f32 v[66:67], v[62:63], v[50:51]
	v_pk_mul_f32 v[50:51], v[58:59], v[50:51]
	v_pk_fma_f32 v[48:49], v[60:61], v[52:53], v[48:49]
	v_pk_fma_f32 v[66:67], v[58:59], v[54:55], v[66:67] neg_lo:[0,0,1] neg_hi:[0,0,1]
	v_pk_fma_f32 v[50:51], v[62:63], v[54:55], v[50:51]
	v_pk_mul_f32 v[54:55], v[128:129], v[48:49] op_sel_hi:[0,1]
	v_ashrrev_i32_e32 v48, 10, v64
	v_and_or_b32 v48, v48, -4, s48
	v_ashrrev_i32_e32 v49, 31, v48
	v_pk_fma_f32 v[68:69], v[56:57], v[52:53], v[68:69] neg_lo:[0,0,1] neg_hi:[0,0,1]
	v_lshlrev_b64 v[56:57], 9, v[48:49]
	v_lshrrev_b32_e32 v48, 3, v64
	v_and_or_b32 v56, v48, s4, v56
	v_mad_i64_i32 v[58:59], s[20:21], v64, s5, v[112:113]
	v_lshl_add_u64 v[60:61], v[56:57], 0, v[116:117]
	v_lshl_add_u64 v[58:59], v[58:59], 0, s[58:59]
	v_lshlrev_b64 v[60:61], 10, v[60:61]
	v_lshl_add_u64 v[58:59], v[58:59], 0, s[28:29]
	v_lshl_add_u64 v[60:61], s[92:93], 0, v[60:61]
	v_pk_mul_f32 v[52:53], v[128:129], v[50:51] op_sel_hi:[0,1]
	v_cvt_pk_bf16_f32 v48, v80, v81
	v_cvt_pk_bf16_f32 v49, v76, v77
	v_cvt_pk_bf16_f32 v50, v82, v83
	v_cvt_pk_bf16_f32 v51, v78, v79
	v_lshl_add_u64 v[58:59], v[58:59], 0, v[114:115]
	v_lshl_add_u64 v[60:61], v[60:61], 0, v[188:189]
	v_permlane16_swap_b32_e32 v48, v50
	v_permlane16_swap_b32_e32 v49, v51
	v_cndmask_b32_e32 v61, v59, v61, vcc
	v_cndmask_b32_e32 v60, v58, v60, vcc
	v_pk_mul_f32 v[66:67], v[128:129], v[66:67] op_sel_hi:[0,1]
	v_pk_mul_f32 v[68:69], v[128:129], v[68:69] op_sel_hi:[0,1]
	global_store_dwordx4 v[60:61], v[48:51], off
	s_mov_b64 s[20:21], s[40:41]
	s_nop 0
	v_cvt_pk_bf16_f32 v48, v68, v69
	v_cvt_pk_bf16_f32 v49, v66, v67
	v_cvt_pk_bf16_f32 v50, v54, v55
	v_lshl_add_u64 v[54:55], v[56:57], 0, v[118:119]
	v_lshlrev_b64 v[54:55], 10, v[54:55]
	v_lshl_add_u64 v[54:55], s[92:93], 0, v[54:55]
	v_cvt_pk_bf16_f32 v51, v52, v53
	v_lshl_add_u64 v[52:53], v[58:59], 0, 64
	v_lshl_add_u64 v[54:55], v[54:55], 0, v[188:189]
	v_permlane16_swap_b32_e32 v48, v50
	v_permlane16_swap_b32_e32 v49, v51
	v_cndmask_b32_e32 v53, v53, v55, vcc
	v_cndmask_b32_e32 v52, v52, v54, vcc
	global_store_dwordx4 v[52:53], v[48:51], off
	s_nop 1
	v_add_u32_e32 v48, 0x90, v140
	v_ashrrev_i32_e32 v49, 31, v48
	v_lshlrev_b64 v[50:51], 6, v[48:49]
	v_lshl_add_u64 v[50:51], s[96:97], 0, v[50:51]
	v_lshl_add_u64 v[50:51], v[50:51], 0, v[144:145]
	v_mov_b32_e32 v50, v232
	v_mov_b32_e32 v51, v233
	v_mov_b32_e32 v52, v234
	v_mov_b32_e32 v53, v235
	v_and_b32_e32 v188, 0xfc0, v48
	v_mov_b32_e32 v54, v51
	v_mov_b32_e32 v55, v52
	v_mov_b32_e32 v51, v53
	v_pk_add_f32 v[50:51], v[54:55], v[50:51]
	s_nop 0
	v_add_f32_e32 v49, v50, v51
	ds_bpermute_b32 v50, v170, v49
	s_waitcnt lgkmcnt(0)
	v_add_f32_e32 v49, v49, v50
	ds_bpermute_b32 v50, v171, v49
	s_waitcnt lgkmcnt(0)
	v_add_f32_e32 v49, v49, v50
	v_fmamk_f32 v49, v49, 0x3a800000, v209
	v_cmp_gt_f32_e64 s[38:39], s0, v49
	v_mul_f32_e32 v50, 0x4b800000, v49
	s_nop 0
	v_cndmask_b32_e64 v49, v49, v50, s[38:39]
	v_rsq_f32_e32 v49, v49
	s_nop 0
	v_mul_f32_e32 v50, 0x45800000, v49
	v_cndmask_b32_e64 v52, v49, v50, s[38:39]
	v_pk_mul_f32 v[44:45], v[44:45], v[52:53] op_sel_hi:[1,0]
	v_pk_mul_f32 v[46:47], v[46:47], v[52:53] op_sel_hi:[1,0]
	v_pk_mul_f32 v[68:69], v[44:45], v[44:45]
	v_pk_mul_f32 v[58:59], v[46:47], v[46:47]
	v_pk_mul_f32 v[40:41], v[40:41], v[52:53] op_sel_hi:[1,0]
	v_pk_mov_b32 v[70:71], v[68:69], v[58:59] op_sel:[1,0]
	v_mov_b32_e32 v69, v59
	v_pk_mul_f32 v[42:43], v[42:43], v[52:53] op_sel_hi:[1,0]
	v_pk_add_f32 v[58:59], v[70:71], v[68:69]
	v_pk_mul_f32 v[56:57], v[36:37], v[52:53] op_sel_hi:[1,0]
	v_pk_add_f32 v[58:59], v[58:59], v[58:59] op_sel_hi:[0,1]
	v_pk_mul_f32 v[68:69], v[42:43], v[42:43]
	v_pk_mul_f32 v[70:71], v[40:41], v[40:41]
	v_pk_mul_f32 v[54:55], v[38:39], v[52:53] op_sel_hi:[1,0]
	v_pk_mov_b32 v[72:73], v[70:71], v[68:69] op_sel:[1,0]
	v_mov_b32_e32 v71, v69
	v_mul_f32_e32 v58, v56, v56
	v_pk_add_f32 v[68:69], v[72:73], v[70:71]
	v_pk_fma_f32 v[70:71], v[56:57], v[56:57], v[58:59] op_sel_hi:[1,1,0]
	v_mul_f32_e32 v58, v54, v54
	v_pk_mul_f32 v[50:51], v[34:35], v[52:53] op_sel_hi:[1,0]
	v_pk_mul_f32 v[52:53], v[32:33], v[52:53] op_sel_hi:[1,0]
	v_pk_add_f32 v[68:69], v[68:69], v[68:69] op_sel_hi:[0,1]
	v_pk_fma_f32 v[72:73], v[54:55], v[54:55], v[58:59] op_sel_hi:[1,1,0]
	v_mul_f32_e32 v70, v52, v52
	v_mul_f32_e32 v72, v53, v53
	v_mul_f32_e32 v58, v50, v50
	v_mul_f32_e32 v68, v51, v51
	v_lshl_add_u64 v[32:33], s[20:21], 0, v[144:145]
	v_pk_add_f32 v[70:71], v[70:71], v[72:73]
	v_pk_add_f32 v[58:59], v[58:59], v[68:69]
	v_lshl_add_u64 v[68:69], v[142:143], 0, v[188:189]
	v_lshl_add_u64 v[72:73], v[130:131], 0, v[188:189]
	flat_load_dwordx4 v[60:63], v[32:33]
	flat_load_dwordx4 v[64:67], v[32:33] offset:64
	flat_load_dwordx4 v[36:39], v[32:33] offset:128
	s_nop 0
	flat_load_dwordx4 v[32:35], v[32:33] offset:192
	v_pk_add_f32 v[58:59], v[70:71], v[58:59]
	global_load_dwordx4 v[68:71], v[68:69], off
	v_add_f32_e32 v49, v58, v59
	global_load_dwordx4 v[72:75], v[72:73], off
	ds_bpermute_b32 v58, v170, v49
	s_waitcnt lgkmcnt(0)
	v_add_f32_e32 v49, v49, v58
	ds_bpermute_b32 v58, v171, v49
	s_waitcnt lgkmcnt(0)
	v_add_f32_e32 v49, v49, v58
	v_fmamk_f32 v49, v49, 0x3c800000, v209
	v_cmp_gt_f32_e64 s[38:39], s0, v49
	v_mul_f32_e32 v58, 0x4b800000, v49
	s_nop 0
	v_cndmask_b32_e64 v49, v49, v58, s[38:39]
	v_rsq_f32_e32 v49, v49
	s_nop 0
	v_mul_f32_e32 v58, 0x45800000, v49
	v_cndmask_b32_e64 v58, v49, v58, s[38:39]
	v_pk_mul_f32 v[40:41], v[40:41], v[58:59] op_sel_hi:[1,0]
	v_pk_mul_f32 v[44:45], v[44:45], v[58:59] op_sel_hi:[1,0]
	v_pk_mul_f32 v[46:47], v[46:47], v[58:59] op_sel_hi:[1,0]
	v_pk_mul_f32 v[42:43], v[42:43], v[58:59] op_sel_hi:[1,0]
	v_pk_mul_f32 v[52:53], v[52:53], v[58:59] op_sel_hi:[1,0]
	v_pk_mul_f32 v[56:57], v[56:57], v[58:59] op_sel_hi:[1,0]
	v_pk_mul_f32 v[50:51], v[50:51], v[58:59] op_sel_hi:[1,0]
	v_pk_mul_f32 v[54:55], v[54:55], v[58:59] op_sel_hi:[1,0]
	s_waitcnt vmcnt(0)
	v_pk_mul_f32 v[46:47], v[62:63], v[46:47]
	v_pk_mul_f32 v[40:41], v[64:65], v[40:41]
	v_pk_mul_f32 v[44:45], v[60:61], v[44:45]
	v_pk_mul_f32 v[42:43], v[66:67], v[42:43]
	v_pk_mul_f32 v[32:33], v[32:33], v[52:53]
	v_pk_mul_f32 v[36:37], v[36:37], v[56:57]
	v_pk_mul_f32 v[34:35], v[34:35], v[50:51]
	v_pk_mul_f32 v[62:63], v[72:73], v[40:41]
	v_pk_mul_f32 v[40:41], v[68:69], v[40:41]
	v_pk_mul_f32 v[60:61], v[74:75], v[42:43]
	v_pk_fma_f32 v[40:41], v[72:73], v[44:45], v[40:41]
	v_pk_fma_f32 v[62:63], v[68:69], v[44:45], v[62:63] neg_lo:[0,0,1] neg_hi:[0,0,1]
	v_pk_mul_f32 v[66:67], v[128:129], v[40:41] op_sel_hi:[0,1]
	v_lshlrev_b32_e32 v40, 4, v48
	v_and_b32_e32 v188, 0x3f0, v40
	v_pk_mul_f32 v[42:43], v[70:71], v[42:43]
	v_lshlrev_b32_e32 v44, 2, v188
	v_mov_b32_e32 v45, v189
	v_pk_fma_f32 v[42:43], v[74:75], v[46:47], v[42:43]
	v_lshl_add_u64 v[40:41], v[142:143], 0, v[44:45]
	v_lshl_add_u64 v[44:45], v[130:131], 0, v[44:45]
	v_pk_fma_f32 v[60:61], v[70:71], v[46:47], v[60:61] neg_lo:[0,0,1] neg_hi:[0,0,1]
	v_pk_mul_f32 v[64:65], v[128:129], v[62:63] op_sel_hi:[0,1]
	v_pk_mul_f32 v[62:63], v[128:129], v[42:43] op_sel_hi:[0,1]
	global_load_dwordx4 v[40:43], v[40:41], off
	v_pk_mul_f32 v[38:39], v[38:39], v[54:55]
	global_load_dwordx4 v[44:47], v[44:45], off
	v_pk_mul_f32 v[60:61], v[128:129], v[60:61] op_sel_hi:[0,1]
	s_waitcnt vmcnt(0)
	v_pk_mul_f32 v[52:53], v[44:45], v[32:33]
	v_pk_mul_f32 v[32:33], v[40:41], v[32:33]
	v_pk_mul_f32 v[50:51], v[46:47], v[34:35]
	v_pk_mul_f32 v[34:35], v[42:43], v[34:35]
	v_pk_fma_f32 v[32:33], v[44:45], v[36:37], v[32:33]
	v_pk_fma_f32 v[50:51], v[42:43], v[38:39], v[50:51] neg_lo:[0,0,1] neg_hi:[0,0,1]
	v_pk_fma_f32 v[34:35], v[46:47], v[38:39], v[34:35]
	v_pk_mul_f32 v[38:39], v[128:129], v[32:33] op_sel_hi:[0,1]
	v_ashrrev_i32_e32 v32, 10, v48
	v_and_or_b32 v32, v32, -4, s48
	v_ashrrev_i32_e32 v33, 31, v32
	v_pk_fma_f32 v[52:53], v[40:41], v[36:37], v[52:53] neg_lo:[0,0,1] neg_hi:[0,0,1]
	v_lshlrev_b64 v[40:41], 9, v[32:33]
	v_lshrrev_b32_e32 v32, 3, v48
	v_and_or_b32 v40, v32, s4, v40
	v_mad_i64_i32 v[42:43], s[20:21], v48, s5, v[112:113]
	v_lshl_add_u64 v[44:45], v[40:41], 0, v[116:117]
	v_lshl_add_u64 v[42:43], v[42:43], 0, s[58:59]
	v_lshlrev_b64 v[44:45], 10, v[44:45]
	v_lshl_add_u64 v[42:43], v[42:43], 0, s[28:29]
	v_lshl_add_u64 v[44:45], s[92:93], 0, v[44:45]
	v_pk_mul_f32 v[36:37], v[128:129], v[34:35] op_sel_hi:[0,1]
	v_cvt_pk_bf16_f32 v32, v64, v65
	v_cvt_pk_bf16_f32 v33, v60, v61
	v_cvt_pk_bf16_f32 v34, v66, v67
	v_cvt_pk_bf16_f32 v35, v62, v63
	v_lshl_add_u64 v[42:43], v[42:43], 0, v[114:115]
	v_lshl_add_u64 v[44:45], v[44:45], 0, v[188:189]
	v_permlane16_swap_b32_e32 v32, v34
	v_permlane16_swap_b32_e32 v33, v35
	v_cndmask_b32_e32 v45, v43, v45, vcc
	v_cndmask_b32_e32 v44, v42, v44, vcc
	v_pk_mul_f32 v[50:51], v[128:129], v[50:51] op_sel_hi:[0,1]
	v_pk_mul_f32 v[52:53], v[128:129], v[52:53] op_sel_hi:[0,1]
	global_store_dwordx4 v[44:45], v[32:35], off
	s_mov_b64 s[20:21], s[40:41]
	s_nop 0
	v_cvt_pk_bf16_f32 v32, v52, v53
	v_cvt_pk_bf16_f32 v33, v50, v51
	v_cvt_pk_bf16_f32 v34, v38, v39
	v_lshl_add_u64 v[38:39], v[40:41], 0, v[118:119]
	v_lshlrev_b64 v[38:39], 10, v[38:39]
	v_lshl_add_u64 v[38:39], s[92:93], 0, v[38:39]
	v_cvt_pk_bf16_f32 v35, v36, v37
	v_lshl_add_u64 v[36:37], v[42:43], 0, 64
	v_lshl_add_u64 v[38:39], v[38:39], 0, v[188:189]
	v_permlane16_swap_b32_e32 v32, v34
	v_permlane16_swap_b32_e32 v33, v35
	v_cndmask_b32_e32 v37, v37, v39, vcc
	v_cndmask_b32_e32 v36, v36, v38, vcc
	global_store_dwordx4 v[36:37], v[32:35], off
	s_nop 1
	v_add_u32_e32 v32, 0xa0, v140
	v_ashrrev_i32_e32 v33, 31, v32
	v_lshlrev_b64 v[34:35], 6, v[32:33]
	v_lshl_add_u64 v[34:35], s[96:97], 0, v[34:35]
	v_lshl_add_u64 v[34:35], v[34:35], 0, v[144:145]
	v_mov_b32_e32 v34, v236
	v_mov_b32_e32 v35, v237
	v_mov_b32_e32 v36, v238
	v_mov_b32_e32 v37, v239
	v_and_b32_e32 v188, 0xfc0, v32
	v_mov_b32_e32 v38, v35
	v_mov_b32_e32 v39, v36
	v_mov_b32_e32 v35, v37
	v_pk_add_f32 v[34:35], v[38:39], v[34:35]
	s_nop 0
	v_add_f32_e32 v33, v34, v35
	ds_bpermute_b32 v34, v170, v33
	s_waitcnt lgkmcnt(0)
	v_add_f32_e32 v33, v33, v34
	ds_bpermute_b32 v34, v171, v33
	s_waitcnt lgkmcnt(0)
	v_add_f32_e32 v33, v33, v34
	v_fmamk_f32 v33, v33, 0x3a800000, v209
	v_cmp_gt_f32_e64 s[38:39], s0, v33
	v_mul_f32_e32 v34, 0x4b800000, v33
	s_nop 0
	v_cndmask_b32_e64 v33, v33, v34, s[38:39]
	v_rsq_f32_e32 v33, v33
	s_nop 0
	v_mul_f32_e32 v34, 0x45800000, v33
	v_cndmask_b32_e64 v36, v33, v34, s[38:39]
	v_pk_mul_f32 v[28:29], v[28:29], v[36:37] op_sel_hi:[1,0]
	v_pk_mul_f32 v[30:31], v[30:31], v[36:37] op_sel_hi:[1,0]
	v_pk_mul_f32 v[52:53], v[28:29], v[28:29]
	v_pk_mul_f32 v[42:43], v[30:31], v[30:31]
	v_pk_mul_f32 v[24:25], v[24:25], v[36:37] op_sel_hi:[1,0]
	v_pk_mov_b32 v[54:55], v[52:53], v[42:43] op_sel:[1,0]
	v_mov_b32_e32 v53, v43
	v_pk_mul_f32 v[26:27], v[26:27], v[36:37] op_sel_hi:[1,0]
	v_pk_add_f32 v[42:43], v[54:55], v[52:53]
	v_pk_mul_f32 v[40:41], v[20:21], v[36:37] op_sel_hi:[1,0]
	v_pk_add_f32 v[42:43], v[42:43], v[42:43] op_sel_hi:[0,1]
	v_pk_mul_f32 v[52:53], v[26:27], v[26:27]
	v_pk_mul_f32 v[54:55], v[24:25], v[24:25]
	v_pk_mul_f32 v[38:39], v[22:23], v[36:37] op_sel_hi:[1,0]
	v_pk_mov_b32 v[56:57], v[54:55], v[52:53] op_sel:[1,0]
	v_mov_b32_e32 v55, v53
	v_mul_f32_e32 v42, v40, v40
	v_pk_add_f32 v[52:53], v[56:57], v[54:55]
	v_pk_fma_f32 v[54:55], v[40:41], v[40:41], v[42:43] op_sel_hi:[1,1,0]
	v_mul_f32_e32 v42, v38, v38
	v_pk_mul_f32 v[34:35], v[18:19], v[36:37] op_sel_hi:[1,0]
	v_pk_mul_f32 v[36:37], v[16:17], v[36:37] op_sel_hi:[1,0]
	v_pk_add_f32 v[52:53], v[52:53], v[52:53] op_sel_hi:[0,1]
	v_pk_fma_f32 v[56:57], v[38:39], v[38:39], v[42:43] op_sel_hi:[1,1,0]
	v_mul_f32_e32 v54, v36, v36
	v_mul_f32_e32 v56, v37, v37
	v_mul_f32_e32 v42, v34, v34
	v_mul_f32_e32 v52, v35, v35
	v_lshl_add_u64 v[16:17], s[20:21], 0, v[144:145]
	v_pk_add_f32 v[54:55], v[54:55], v[56:57]
	v_pk_add_f32 v[42:43], v[42:43], v[52:53]
	v_lshl_add_u64 v[52:53], v[142:143], 0, v[188:189]
	v_lshl_add_u64 v[56:57], v[130:131], 0, v[188:189]
	flat_load_dwordx4 v[44:47], v[16:17]
	flat_load_dwordx4 v[48:51], v[16:17] offset:64
	flat_load_dwordx4 v[20:23], v[16:17] offset:128
	s_nop 0
	flat_load_dwordx4 v[16:19], v[16:17] offset:192
	v_pk_add_f32 v[42:43], v[54:55], v[42:43]
	global_load_dwordx4 v[52:55], v[52:53], off
	v_add_f32_e32 v33, v42, v43
	global_load_dwordx4 v[56:59], v[56:57], off
	ds_bpermute_b32 v42, v170, v33
	s_waitcnt lgkmcnt(0)
	v_add_f32_e32 v33, v33, v42
	ds_bpermute_b32 v42, v171, v33
	s_waitcnt lgkmcnt(0)
	v_add_f32_e32 v33, v33, v42
	v_fmamk_f32 v33, v33, 0x3c800000, v209
	v_cmp_gt_f32_e64 s[38:39], s0, v33
	v_mul_f32_e32 v42, 0x4b800000, v33
	s_nop 0
	v_cndmask_b32_e64 v33, v33, v42, s[38:39]
	v_rsq_f32_e32 v33, v33
	s_nop 0
	v_mul_f32_e32 v42, 0x45800000, v33
	v_cndmask_b32_e64 v42, v33, v42, s[38:39]
	v_pk_mul_f32 v[24:25], v[24:25], v[42:43] op_sel_hi:[1,0]
	v_pk_mul_f32 v[28:29], v[28:29], v[42:43] op_sel_hi:[1,0]
	v_pk_mul_f32 v[30:31], v[30:31], v[42:43] op_sel_hi:[1,0]
	v_pk_mul_f32 v[26:27], v[26:27], v[42:43] op_sel_hi:[1,0]
	v_pk_mul_f32 v[36:37], v[36:37], v[42:43] op_sel_hi:[1,0]
	v_pk_mul_f32 v[40:41], v[40:41], v[42:43] op_sel_hi:[1,0]
	v_pk_mul_f32 v[34:35], v[34:35], v[42:43] op_sel_hi:[1,0]
	v_pk_mul_f32 v[38:39], v[38:39], v[42:43] op_sel_hi:[1,0]
	s_waitcnt vmcnt(0)
	v_pk_mul_f32 v[30:31], v[46:47], v[30:31]
	v_pk_mul_f32 v[24:25], v[48:49], v[24:25]
	v_pk_mul_f32 v[28:29], v[44:45], v[28:29]
	v_pk_mul_f32 v[26:27], v[50:51], v[26:27]
	v_pk_mul_f32 v[16:17], v[16:17], v[36:37]
	v_pk_mul_f32 v[20:21], v[20:21], v[40:41]
	v_pk_mul_f32 v[18:19], v[18:19], v[34:35]
	v_pk_mul_f32 v[46:47], v[56:57], v[24:25]
	v_pk_mul_f32 v[24:25], v[52:53], v[24:25]
	v_pk_mul_f32 v[44:45], v[58:59], v[26:27]
	v_pk_fma_f32 v[24:25], v[56:57], v[28:29], v[24:25]
	v_pk_fma_f32 v[46:47], v[52:53], v[28:29], v[46:47] neg_lo:[0,0,1] neg_hi:[0,0,1]
	v_pk_mul_f32 v[50:51], v[128:129], v[24:25] op_sel_hi:[0,1]
	v_lshlrev_b32_e32 v24, 4, v32
	v_and_b32_e32 v188, 0x3f0, v24
	v_pk_mul_f32 v[26:27], v[54:55], v[26:27]
	v_lshlrev_b32_e32 v28, 2, v188
	v_mov_b32_e32 v29, v189
	v_pk_fma_f32 v[26:27], v[58:59], v[30:31], v[26:27]
	v_lshl_add_u64 v[24:25], v[142:143], 0, v[28:29]
	v_lshl_add_u64 v[28:29], v[130:131], 0, v[28:29]
	v_pk_fma_f32 v[44:45], v[54:55], v[30:31], v[44:45] neg_lo:[0,0,1] neg_hi:[0,0,1]
	v_pk_mul_f32 v[48:49], v[128:129], v[46:47] op_sel_hi:[0,1]
	v_pk_mul_f32 v[46:47], v[128:129], v[26:27] op_sel_hi:[0,1]
	global_load_dwordx4 v[24:27], v[24:25], off
	v_pk_mul_f32 v[22:23], v[22:23], v[38:39]
	global_load_dwordx4 v[28:31], v[28:29], off
	v_pk_mul_f32 v[44:45], v[128:129], v[44:45] op_sel_hi:[0,1]
	s_waitcnt vmcnt(0)
	v_pk_mul_f32 v[36:37], v[28:29], v[16:17]
	v_pk_mul_f32 v[16:17], v[24:25], v[16:17]
	v_pk_mul_f32 v[34:35], v[30:31], v[18:19]
	v_pk_mul_f32 v[18:19], v[26:27], v[18:19]
	v_pk_fma_f32 v[16:17], v[28:29], v[20:21], v[16:17]
	v_pk_fma_f32 v[34:35], v[26:27], v[22:23], v[34:35] neg_lo:[0,0,1] neg_hi:[0,0,1]
	v_pk_fma_f32 v[18:19], v[30:31], v[22:23], v[18:19]
	v_pk_mul_f32 v[22:23], v[128:129], v[16:17] op_sel_hi:[0,1]
	v_ashrrev_i32_e32 v16, 10, v32
	v_and_or_b32 v16, v16, -4, s48
	v_ashrrev_i32_e32 v17, 31, v16
	v_pk_fma_f32 v[36:37], v[24:25], v[20:21], v[36:37] neg_lo:[0,0,1] neg_hi:[0,0,1]
	v_lshlrev_b64 v[24:25], 9, v[16:17]
	v_lshrrev_b32_e32 v16, 3, v32
	v_and_or_b32 v24, v16, s4, v24
	v_mad_i64_i32 v[26:27], s[20:21], v32, s5, v[112:113]
	v_lshl_add_u64 v[28:29], v[24:25], 0, v[116:117]
	v_lshl_add_u64 v[26:27], v[26:27], 0, s[58:59]
	v_lshlrev_b64 v[28:29], 10, v[28:29]
	v_lshl_add_u64 v[26:27], v[26:27], 0, s[28:29]
	v_lshl_add_u64 v[28:29], s[92:93], 0, v[28:29]
	v_pk_mul_f32 v[20:21], v[128:129], v[18:19] op_sel_hi:[0,1]
	v_cvt_pk_bf16_f32 v16, v48, v49
	v_cvt_pk_bf16_f32 v17, v44, v45
	v_cvt_pk_bf16_f32 v18, v50, v51
	v_cvt_pk_bf16_f32 v19, v46, v47
	v_lshl_add_u64 v[26:27], v[26:27], 0, v[114:115]
	v_lshl_add_u64 v[28:29], v[28:29], 0, v[188:189]
	v_permlane16_swap_b32_e32 v16, v18
	v_permlane16_swap_b32_e32 v17, v19
	v_cndmask_b32_e32 v29, v27, v29, vcc
	v_cndmask_b32_e32 v28, v26, v28, vcc
	v_pk_mul_f32 v[34:35], v[128:129], v[34:35] op_sel_hi:[0,1]
	v_pk_mul_f32 v[36:37], v[128:129], v[36:37] op_sel_hi:[0,1]
	global_store_dwordx4 v[28:29], v[16:19], off
	s_nop 1
	v_cvt_pk_bf16_f32 v16, v36, v37
	v_cvt_pk_bf16_f32 v17, v34, v35
	v_cvt_pk_bf16_f32 v18, v22, v23
	v_lshl_add_u64 v[22:23], v[24:25], 0, v[118:119]
	v_lshlrev_b64 v[22:23], 10, v[22:23]
	v_lshl_add_u64 v[22:23], s[92:93], 0, v[22:23]
	v_cvt_pk_bf16_f32 v19, v20, v21
	v_lshl_add_u64 v[20:21], v[26:27], 0, 64
	v_lshl_add_u64 v[22:23], v[22:23], 0, v[188:189]
	v_permlane16_swap_b32_e32 v16, v18
	v_permlane16_swap_b32_e32 v17, v19
	v_cndmask_b32_e32 v21, v21, v23, vcc
	v_cndmask_b32_e32 v20, v20, v22, vcc
	global_store_dwordx4 v[20:21], v[16:19], off
	s_nop 1
	v_add_u32_e32 v16, 0xb0, v140
	v_ashrrev_i32_e32 v17, 31, v16
	v_lshlrev_b64 v[18:19], 6, v[16:17]
	v_lshl_add_u64 v[18:19], s[96:97], 0, v[18:19]
	v_lshl_add_u64 v[18:19], v[18:19], 0, v[144:145]
	v_mov_b32_e32 v18, v240
	v_mov_b32_e32 v19, v241
	v_mov_b32_e32 v20, v242
	v_mov_b32_e32 v21, v243
	v_and_b32_e32 v188, 0xfc0, v16
	v_mov_b32_e32 v22, v19
	v_mov_b32_e32 v23, v20
	v_mov_b32_e32 v19, v21
	v_pk_add_f32 v[18:19], v[22:23], v[18:19]
	s_nop 0
	v_add_f32_e32 v17, v18, v19
	ds_bpermute_b32 v18, v170, v17
	s_waitcnt lgkmcnt(0)
	v_add_f32_e32 v17, v17, v18
	ds_bpermute_b32 v18, v171, v17
	s_waitcnt lgkmcnt(0)
	v_add_f32_e32 v17, v17, v18
	v_fmamk_f32 v17, v17, 0x3a800000, v209
	v_cmp_gt_f32_e64 s[38:39], s0, v17
	v_mul_f32_e32 v18, 0x4b800000, v17
	s_nop 0
	v_cndmask_b32_e64 v17, v17, v18, s[38:39]
	v_rsq_f32_e32 v17, v17
	s_nop 0
	v_mul_f32_e32 v18, 0x45800000, v17
	v_cndmask_b32_e64 v20, v17, v18, s[38:39]
	v_pk_mul_f32 v[12:13], v[12:13], v[20:21] op_sel_hi:[1,0]
	v_pk_mul_f32 v[14:15], v[14:15], v[20:21] op_sel_hi:[1,0]
	v_pk_mul_f32 v[36:37], v[12:13], v[12:13]
	v_pk_mul_f32 v[26:27], v[14:15], v[14:15]
	v_pk_mul_f32 v[8:9], v[8:9], v[20:21] op_sel_hi:[1,0]
	v_pk_mov_b32 v[38:39], v[36:37], v[26:27] op_sel:[1,0]
	v_mov_b32_e32 v37, v27
	v_pk_mul_f32 v[10:11], v[10:11], v[20:21] op_sel_hi:[1,0]
	v_pk_add_f32 v[26:27], v[38:39], v[36:37]
	v_pk_mul_f32 v[24:25], v[4:5], v[20:21] op_sel_hi:[1,0]
	v_pk_add_f32 v[26:27], v[26:27], v[26:27] op_sel_hi:[0,1]
	v_pk_mul_f32 v[36:37], v[10:11], v[10:11]
	v_pk_mul_f32 v[38:39], v[8:9], v[8:9]
	v_pk_mul_f32 v[22:23], v[6:7], v[20:21] op_sel_hi:[1,0]
	v_pk_mov_b32 v[40:41], v[38:39], v[36:37] op_sel:[1,0]
	v_mov_b32_e32 v39, v37
	v_mul_f32_e32 v26, v24, v24
	v_pk_add_f32 v[36:37], v[40:41], v[38:39]
	v_pk_fma_f32 v[38:39], v[24:25], v[24:25], v[26:27] op_sel_hi:[1,1,0]
	v_mul_f32_e32 v26, v22, v22
	v_pk_mul_f32 v[18:19], v[2:3], v[20:21] op_sel_hi:[1,0]
	v_pk_mul_f32 v[20:21], v[0:1], v[20:21] op_sel_hi:[1,0]
	v_pk_add_f32 v[36:37], v[36:37], v[36:37] op_sel_hi:[0,1]
	v_pk_fma_f32 v[40:41], v[22:23], v[22:23], v[26:27] op_sel_hi:[1,1,0]
	v_mul_f32_e32 v38, v20, v20
	v_mul_f32_e32 v40, v21, v21
	v_mul_f32_e32 v26, v18, v18
	v_mul_f32_e32 v36, v19, v19
	v_lshl_add_u64 v[0:1], s[40:41], 0, v[144:145]
	v_pk_add_f32 v[38:39], v[38:39], v[40:41]
	v_pk_add_f32 v[26:27], v[26:27], v[36:37]
	v_lshl_add_u64 v[36:37], v[142:143], 0, v[188:189]
	v_lshl_add_u64 v[40:41], v[130:131], 0, v[188:189]
	flat_load_dwordx4 v[28:31], v[0:1]
	flat_load_dwordx4 v[32:35], v[0:1] offset:64
	flat_load_dwordx4 v[4:7], v[0:1] offset:128
	s_nop 0
	flat_load_dwordx4 v[0:3], v[0:1] offset:192
	v_pk_add_f32 v[26:27], v[38:39], v[26:27]
	global_load_dwordx4 v[36:39], v[36:37], off
	v_add_f32_e32 v17, v26, v27
	global_load_dwordx4 v[40:43], v[40:41], off
	ds_bpermute_b32 v26, v170, v17
	s_waitcnt lgkmcnt(0)
	v_add_f32_e32 v17, v17, v26
	ds_bpermute_b32 v26, v171, v17
	s_waitcnt lgkmcnt(0)
	v_add_f32_e32 v17, v17, v26
	v_fmamk_f32 v17, v17, 0x3c800000, v209
	v_cmp_gt_f32_e64 s[38:39], s0, v17
	v_mul_f32_e32 v26, 0x4b800000, v17
	s_nop 0
	v_cndmask_b32_e64 v17, v17, v26, s[38:39]
	v_rsq_f32_e32 v17, v17
	s_nop 0
	v_mul_f32_e32 v26, 0x45800000, v17
	v_cndmask_b32_e64 v26, v17, v26, s[38:39]
	v_pk_mul_f32 v[8:9], v[8:9], v[26:27] op_sel_hi:[1,0]
	v_pk_mul_f32 v[12:13], v[12:13], v[26:27] op_sel_hi:[1,0]
	v_pk_mul_f32 v[14:15], v[14:15], v[26:27] op_sel_hi:[1,0]
	v_pk_mul_f32 v[10:11], v[10:11], v[26:27] op_sel_hi:[1,0]
	v_pk_mul_f32 v[20:21], v[20:21], v[26:27] op_sel_hi:[1,0]
	v_pk_mul_f32 v[24:25], v[24:25], v[26:27] op_sel_hi:[1,0]
	v_pk_mul_f32 v[18:19], v[18:19], v[26:27] op_sel_hi:[1,0]
	v_pk_mul_f32 v[22:23], v[22:23], v[26:27] op_sel_hi:[1,0]
	s_waitcnt vmcnt(0)
	v_pk_mul_f32 v[14:15], v[30:31], v[14:15]
	v_pk_mul_f32 v[8:9], v[32:33], v[8:9]
	v_pk_mul_f32 v[12:13], v[28:29], v[12:13]
	v_pk_mul_f32 v[10:11], v[34:35], v[10:11]
	v_pk_mul_f32 v[0:1], v[0:1], v[20:21]
	v_pk_mul_f32 v[4:5], v[4:5], v[24:25]
	v_pk_mul_f32 v[2:3], v[2:3], v[18:19]
	v_pk_mul_f32 v[30:31], v[40:41], v[8:9]
	v_pk_mul_f32 v[8:9], v[36:37], v[8:9]
	v_pk_mul_f32 v[28:29], v[42:43], v[10:11]
	v_pk_fma_f32 v[8:9], v[40:41], v[12:13], v[8:9]
	v_pk_fma_f32 v[30:31], v[36:37], v[12:13], v[30:31] neg_lo:[0,0,1] neg_hi:[0,0,1]
	v_pk_mul_f32 v[34:35], v[128:129], v[8:9] op_sel_hi:[0,1]
	v_lshlrev_b32_e32 v8, 4, v16
	v_and_b32_e32 v188, 0x3f0, v8
	v_pk_mul_f32 v[10:11], v[38:39], v[10:11]
	v_lshlrev_b32_e32 v12, 2, v188
	v_mov_b32_e32 v13, v189
	v_pk_fma_f32 v[10:11], v[42:43], v[14:15], v[10:11]
	v_lshl_add_u64 v[8:9], v[142:143], 0, v[12:13]
	v_lshl_add_u64 v[12:13], v[130:131], 0, v[12:13]
	v_pk_fma_f32 v[28:29], v[38:39], v[14:15], v[28:29] neg_lo:[0,0,1] neg_hi:[0,0,1]
	v_pk_mul_f32 v[32:33], v[128:129], v[30:31] op_sel_hi:[0,1]
	v_pk_mul_f32 v[30:31], v[128:129], v[10:11] op_sel_hi:[0,1]
	global_load_dwordx4 v[8:11], v[8:9], off
	v_pk_mul_f32 v[6:7], v[6:7], v[22:23]
	global_load_dwordx4 v[12:15], v[12:13], off
	v_pk_mul_f32 v[28:29], v[128:129], v[28:29] op_sel_hi:[0,1]
	s_waitcnt vmcnt(0)
	v_pk_mul_f32 v[20:21], v[12:13], v[0:1]
	v_pk_mul_f32 v[0:1], v[8:9], v[0:1]
	v_pk_mul_f32 v[18:19], v[14:15], v[2:3]
	v_pk_mul_f32 v[2:3], v[10:11], v[2:3]
	v_pk_fma_f32 v[0:1], v[12:13], v[4:5], v[0:1]
	v_pk_fma_f32 v[18:19], v[10:11], v[6:7], v[18:19] neg_lo:[0,0,1] neg_hi:[0,0,1]
	v_pk_fma_f32 v[2:3], v[14:15], v[6:7], v[2:3]
	v_pk_mul_f32 v[6:7], v[128:129], v[0:1] op_sel_hi:[0,1]
	v_ashrrev_i32_e32 v0, 10, v16
	v_and_or_b32 v0, v0, -4, s48
	v_ashrrev_i32_e32 v1, 31, v0
	v_pk_fma_f32 v[20:21], v[8:9], v[4:5], v[20:21] neg_lo:[0,0,1] neg_hi:[0,0,1]
	v_lshlrev_b64 v[8:9], 9, v[0:1]
	v_lshrrev_b32_e32 v0, 3, v16
	v_and_or_b32 v8, v0, s4, v8
	v_mad_i64_i32 v[10:11], s[20:21], v16, s5, v[112:113]
	v_lshl_add_u64 v[12:13], v[8:9], 0, v[116:117]
	v_lshl_add_u64 v[10:11], v[10:11], 0, s[58:59]
	v_lshlrev_b64 v[12:13], 10, v[12:13]
	v_lshl_add_u64 v[10:11], v[10:11], 0, s[28:29]
	v_lshl_add_u64 v[12:13], s[92:93], 0, v[12:13]
	v_pk_mul_f32 v[4:5], v[128:129], v[2:3] op_sel_hi:[0,1]
	v_cvt_pk_bf16_f32 v0, v32, v33
	v_cvt_pk_bf16_f32 v1, v28, v29
	v_cvt_pk_bf16_f32 v2, v34, v35
	v_cvt_pk_bf16_f32 v3, v30, v31
	v_lshl_add_u64 v[10:11], v[10:11], 0, v[114:115]
	v_lshl_add_u64 v[12:13], v[12:13], 0, v[188:189]
	v_permlane16_swap_b32_e32 v0, v2
	v_permlane16_swap_b32_e32 v1, v3
	v_cndmask_b32_e32 v13, v11, v13, vcc
	v_cndmask_b32_e32 v12, v10, v12, vcc
	v_pk_mul_f32 v[18:19], v[128:129], v[18:19] op_sel_hi:[0,1]
	v_pk_mul_f32 v[20:21], v[128:129], v[20:21] op_sel_hi:[0,1]
	global_store_dwordx4 v[12:13], v[0:3], off
	s_nop 1
	v_cvt_pk_bf16_f32 v0, v20, v21
	v_cvt_pk_bf16_f32 v1, v18, v19
	v_cvt_pk_bf16_f32 v2, v6, v7
	v_lshl_add_u64 v[6:7], v[8:9], 0, v[118:119]
	v_lshlrev_b64 v[6:7], 10, v[6:7]
	v_lshl_add_u64 v[6:7], s[92:93], 0, v[6:7]
	v_cvt_pk_bf16_f32 v3, v4, v5
	v_lshl_add_u64 v[4:5], v[10:11], 0, 64
	v_lshl_add_u64 v[6:7], v[6:7], 0, v[188:189]
	v_permlane16_swap_b32_e32 v0, v2
	v_permlane16_swap_b32_e32 v1, v3
	v_cndmask_b32_e32 v5, v5, v7, vcc
	v_cndmask_b32_e32 v4, v4, v6, vcc
	global_store_dwordx4 v[4:5], v[0:3], off
	s_andn2_b64 vcc, exec, s[36:37]
	s_mov_b64 s[36:37], -1
	s_cbranch_vccnz .LBB0_242
